# combined input projection: pair tiles (256 x 256, A panel shared by two weight tiles, second accumulator set parked in LDS during the first epilogue) on chunk-major H / W_in, all waves deferred-MFMA
# baseline (speedup 1.0000x reference)
.LBB0_256:
	s_cbranch_execz .LBB0_371
	v_readlane_b32 s0, v215, 49
	v_readlane_b32 s1, v215, 50
	s_andn2_b64 vcc, exec, s[0:1]
	s_cbranch_vccnz .LBB0_318
	v_readlane_b32 s0, v214, 57
	v_readlane_b32 s1, v214, 58
	s_mov_b32 s2, s0
	s_mul_hi_i32 s1, s0, 0x3500000
	s_mul_i32 s0, s0, 0x3500000
	s_lshl_b32 s12, s2, 4
	s_lshl_b32 s13, s2, 1
	s_add_u32 s2, s48, s0
	s_addc_u32 s3, s49, s1
	s_add_u32 s14, s2, 0x1064e000
	s_addc_u32 s15, s3, 0
	v_readlane_b32 s2, v214, 26
	s_add_u32 s0, s2, s0
	v_readlane_b32 s2, v214, 27
	s_addc_u32 s1, s2, s1
	v_readlane_b32 s16, v214, 12
	v_writelane_b32 v243, 0, 2
	s_branch .LBB0_260
.LBB0_259:
	v_readlane_b32 s3, v243, 2
	s_add_u32 s3, s3, 1
	s_nop 0
	v_writelane_b32 v243, s3, 2
	s_nop 1
.LBB0_260:
	v_readlane_b32 s3, v243, 2
	s_cmp_ge_u32 s3, 5
	s_cbranch_scc1 .LBB0_318
	v_readlane_b32 s38, v214, 12
	v_readlane_b32 s39, v217, 0
	s_and_b32 s39, s39, 7
	s_cmp_eq_u32 s3, 4
	s_cbranch_scc1 .Lgw_u4
	s_lshr_b32 s42, s3, 1
	s_lshl_b32 s42, s42, 5
	s_add_u32 s42, s42, s38
	s_and_b32 s43, s3, 1
	s_mov_b32 s69, s43
	s_branch .Lgw_pq
.Lgw_u4:
	s_mov_b32 s69, 2
	s_cmp_lt_u32 s38, 22
	s_cbranch_scc0 .Lgw_broken
	s_mov_b32 s70, s38
	s_mov_b32 s68, 6
	s_branch .Lgw_set
.Lgw_broken:
	s_sub_u32 s43, s38, 22
	s_lshr_b32 s42, s43, 1
	s_add_u32 s42, s42, 64
	s_and_b32 s43, s43, 1
.Lgw_pq:
	s_mul_i32 s70, s42, 0x5556
	s_lshr_b32 s70, s70, 16
	s_mul_i32 s68, s70, 3
	s_sub_u32 s68, s42, s68
	s_lshl_b32 s68, s68, 1
	s_add_u32 s68, s68, s43
.Lgw_set:
	s_mov_b32 s17, s70
	s_mul_i32 s16, s70, 7
	s_add_u32 s16, s16, s68
	s_lshl_b32 s42, s68, 3
	s_add_u32 s42, s42, s39
	s_add_u32 s42, s42, 16
	s_lshl_b32 s43, s39, 1
	s_add_u32 s43, s43, s68
	s_sub_u32 s18, s43, 3
	s_add_u32 s43, s43, 35
	s_cmp_lt_u32 s68, 5
	s_cselect_b32 s18, s18, s43
	s_cmp_lt_u32 s68, 3
	s_cselect_b32 s18, s42, s18
	s_xor_b32 s68, s68, 1
	s_lshl_b32 s42, s68, 3
	s_add_u32 s42, s42, s39
	s_add_u32 s42, s42, 16
	s_lshl_b32 s43, s39, 1
	s_add_u32 s43, s43, s68
	s_sub_u32 s3, s43, 3
	s_add_u32 s43, s43, 35
	s_cmp_lt_u32 s68, 5
	s_cselect_b32 s3, s3, s43
	s_cmp_lt_u32 s68, 3
	s_cselect_b32 s3, s42, s3
	s_nop 0
	v_writelane_b32 v243, s69, 3
	v_writelane_b32 v243, s3, 4
.LBB0_276:
	v_mov_b32_e32 v0, v142
	v_mov_b32_e32 v2, v142
	s_lshl_b32 s2, s17, 8
	v_lshlrev_b32_e32 v5, 7, v2
	v_lshlrev_b32_e32 v4, 6, v2
	v_and_b32_e32 v31, 0x2000, v5
	v_lshlrev_b32_e32 v5, 2, v2
	v_and_b32_e32 v3, 48, v2
	v_and_b32_e32 v30, 0xffffe000, v4
	v_and_b32_e32 v4, 0x3c0, v4
	v_and_b32_e32 v5, 32, v5
	v_bitop3_b32 v32, v4, v5, v3 bitop3:0x36
	v_ashrrev_i32_e32 v3, 31, v2
	v_lshrrev_b32_e32 v3, 26, v3
	v_lshlrev_b32_e32 v33, 4, v2
	v_add_u32_e32 v3, v2, v3
	v_bfe_i32 v2, v2, 27, 1
	v_lshrrev_b32_e32 v2, 22, v2
	v_add_u32_e32 v2, v33, v2
	v_and_b32_e32 v2, 0xfffffc00, v2
	v_sub_u32_e32 v2, v33, v2
	v_lshrrev_b32_e32 v4, 4, v2
	v_bitop3_b32 v4, v4, v2, 32 bitop3:0x6c
	v_ashrrev_i32_e32 v2, 31, v2
	v_ashrrev_i32_e32 v3, 6, v3
	v_lshrrev_b32_e32 v2, 26, v2
	v_lshlrev_b32_e32 v5, 3, v3
	v_add_u32_e32 v2, v4, v2
	v_and_b32_e32 v5, -16, v5
	v_ashrrev_i32_e32 v6, 6, v2
	v_add_u32_e32 v2, v6, v5
	v_mul_i32_i24_e32 v5, 64, v6
	s_ashr_i32 s3, s2, 31
	v_lshlrev_b32_e32 v3, 5, v3
	v_sub_u32_e32 v4, v4, v5
	s_lshl_b32 s40, s18, 7
	s_lshl_b64 s[4:5], s[2:3], 11
	v_and_b32_e32 v3, 32, v3
	v_ashrrev_i16_sdwa v4, v146, sext(v4) dst_sel:DWORD dst_unused:UNUSED_PAD src0_sel:DWORD src1_sel:BYTE_0
	s_add_u32 s10, s24, s4
	v_add_u32_sdwa v4, v3, sext(v4) dst_sel:DWORD dst_unused:UNUSED_PAD src0_sel:DWORD src1_sel:WORD_0
	v_ashrrev_i32_e32 v3, 31, v2
	s_addc_u32 s11, s25, s5
	v_lshlrev_b64 v[2:3], 11, v[2:3]
	v_ashrrev_i32_e32 v5, 31, v4
	v_add_u32_e32 v78, 0, v33
	v_add_u32_e32 v34, 0x2000, v33
	v_lshl_add_u64 v[6:7], s[10:11], 0, v[2:3]
	v_lshlrev_b64 v[4:5], 1, v[4:5]
	v_readfirstlane_b32 s19, v78
	v_ashrrev_i32_e32 v8, 31, v34
	v_add_u32_e32 v14, 0x2000, v78
	v_add_u32_e32 v35, 0x4000, v33
	v_lshl_add_u64 v[6:7], v[6:7], 0, v[4:5]
	s_mov_b32 m0, s19
	v_lshrrev_b32_e32 v8, 22, v8
	v_readfirstlane_b32 s19, v14
	v_ashrrev_i32_e32 v14, 31, v35
	v_add_u32_e32 v20, 0x4000, v78
	v_add_u32_e32 v36, 0x6000, v33
	s_waitcnt vmcnt(0) lgkmcnt(0)
	s_barrier
	v_add_u32_e32 v8, v34, v8
	s_mov_b32 m0, s19
	v_lshrrev_b32_e32 v14, 22, v14
	v_readfirstlane_b32 s19, v20
	v_ashrrev_i32_e32 v20, 31, v36
	v_ashrrev_i32_e32 v9, 10, v8
	v_add_u32_e32 v14, v35, v14
	v_lshrrev_b32_e32 v20, 22, v20
	v_mul_i32_i24_e32 v8, 0x400, v9
	v_ashrrev_i32_e32 v15, 10, v14
	v_add_u32_e32 v20, v36, v20
	v_sub_u32_e32 v8, v34, v8
	v_mul_i32_i24_e32 v14, 0x400, v15
	v_ashrrev_i32_e32 v21, 10, v20
	v_lshrrev_b32_e32 v10, 4, v8
	v_sub_u32_e32 v14, v35, v14
	v_mul_i32_i24_e32 v20, 0x400, v21
	v_bitop3_b32 v10, v10, v8, 32 bitop3:0x6c
	v_lshrrev_b32_e32 v16, 4, v14
	v_sub_u32_e32 v20, v36, v20
	v_ashrrev_i32_e32 v11, 31, v10
	v_bitop3_b32 v16, v16, v14, 32 bitop3:0x6c
	v_lshrrev_b32_e32 v22, 4, v20
	v_lshrrev_b32_e32 v11, 26, v11
	v_ashrrev_i32_e32 v17, 31, v16
	v_bitop3_b32 v22, v22, v20, 32 bitop3:0x6c
	v_add_u32_e32 v11, v10, v11
	v_lshrrev_b32_e32 v17, 26, v17
	v_ashrrev_i32_e32 v23, 31, v22
	v_lshlrev_b32_e32 v8, 3, v9
	v_ashrrev_i32_e32 v12, 6, v11
	v_and_b32_e32 v11, 0xc0, v11
	v_add_u32_e32 v17, v16, v17
	v_lshrrev_b32_e32 v23, 26, v23
	v_and_b32_e32 v8, -16, v8
	v_lshlrev_b32_e32 v9, 5, v9
	v_sub_u32_e32 v10, v10, v11
	v_lshlrev_b32_e32 v14, 3, v15
	v_ashrrev_i32_e32 v18, 6, v17
	v_and_b32_e32 v17, 0xc0, v17
	v_add_u32_e32 v23, v22, v23
	v_add_u32_e32 v8, v12, v8
	v_and_b32_e32 v9, 32, v9
	v_ashrrev_i16_sdwa v10, v146, sext(v10) dst_sel:DWORD dst_unused:UNUSED_PAD src0_sel:DWORD src1_sel:BYTE_0
	v_and_b32_e32 v14, -16, v14
	v_lshlrev_b32_e32 v15, 5, v15
	v_sub_u32_e32 v16, v16, v17
	v_lshlrev_b32_e32 v20, 3, v21
	v_ashrrev_i32_e32 v24, 6, v23
	v_and_b32_e32 v23, 0xc0, v23
	v_add_u32_sdwa v10, v9, sext(v10) dst_sel:DWORD dst_unused:UNUSED_PAD src0_sel:DWORD src1_sel:WORD_0
	v_ashrrev_i32_e32 v9, 31, v8
	v_add_u32_e32 v14, v18, v14
	v_and_b32_e32 v15, 32, v15
	v_ashrrev_i16_sdwa v16, v146, sext(v16) dst_sel:DWORD dst_unused:UNUSED_PAD src0_sel:DWORD src1_sel:BYTE_0
	v_and_b32_e32 v20, -16, v20
	v_lshlrev_b32_e32 v21, 5, v21
	v_sub_u32_e32 v22, v22, v23
	s_ashr_i32 s41, s40, 31
	v_lshlrev_b64 v[8:9], 11, v[8:9]
	v_ashrrev_i32_e32 v11, 31, v10
	v_add_u32_sdwa v16, v15, sext(v16) dst_sel:DWORD dst_unused:UNUSED_PAD src0_sel:DWORD src1_sel:WORD_0
	v_ashrrev_i32_e32 v15, 31, v14
	v_add_u32_e32 v20, v24, v20
	v_and_b32_e32 v21, 32, v21
	v_ashrrev_i16_sdwa v22, v146, sext(v22) dst_sel:DWORD dst_unused:UNUSED_PAD src0_sel:DWORD src1_sel:BYTE_0
	s_lshl_b64 s[6:7], s[40:41], 11
	v_lshl_add_u64 v[12:13], s[10:11], 0, v[8:9]
	v_lshlrev_b64 v[10:11], 1, v[10:11]
	v_lshlrev_b64 v[14:15], 11, v[14:15]
	v_ashrrev_i32_e32 v17, 31, v16
	v_add_u32_sdwa v22, v21, sext(v22) dst_sel:DWORD dst_unused:UNUSED_PAD src0_sel:DWORD src1_sel:WORD_0
	v_ashrrev_i32_e32 v21, 31, v20
	s_add_u32 s8, s14, s6
	v_lshl_add_u64 v[12:13], v[12:13], 0, v[10:11]
	v_lshl_add_u64 v[18:19], s[10:11], 0, v[14:15]
	v_lshlrev_b64 v[16:17], 1, v[16:17]
	v_lshlrev_b64 v[20:21], 11, v[20:21]
	v_ashrrev_i32_e32 v23, 31, v22
	v_add_u32_e32 v26, 0x6000, v78
	s_addc_u32 s9, s15, s7
	v_lshl_add_u64 v[18:19], v[18:19], 0, v[16:17]
	s_mov_b32 m0, s19
	v_lshl_add_u64 v[24:25], s[10:11], 0, v[20:21]
	v_lshlrev_b64 v[22:23], 1, v[22:23]
	v_readfirstlane_b32 s10, v26
	v_add_u32_e32 v28, 0x8000, v78
	v_lshl_add_u64 v[24:25], v[24:25], 0, v[22:23]
	s_mov_b32 m0, s10
	v_lshl_add_u64 v[26:27], s[8:9], 0, v[2:3]
	v_readfirstlane_b32 s10, v28
	v_add_u32_e32 v37, 0xa000, v78
	v_lshl_add_u64 v[26:27], v[26:27], 0, v[4:5]
	s_mov_b32 m0, s10
	v_lshl_add_u64 v[28:29], s[8:9], 0, v[8:9]
	v_readfirstlane_b32 s8, v37
	v_add_u32_e32 v37, 0xc000, v78
	v_lshl_add_u64 v[28:29], v[28:29], 0, v[10:11]
	s_mov_b32 m0, s8
	v_readfirstlane_b32 s8, v37
	v_lshl_add_u64 v[6:7], v[6:7], 0, s[30:31]
	s_mov_b32 m0, s8
	s_mov_b32 s3, 2
	v_lshl_add_u64 v[6:7], v[12:13], 0, s[30:31]
	v_add_u32_e32 v12, 0xe000, v78
	v_add3_u32 v80, v30, 0, v32
	v_readfirstlane_b32 s8, v12
	s_mov_b32 m0, s8
	s_add_i32 s8, 0, 0xc000
	v_add_u32_e32 v12, s8, v35
	v_readfirstlane_b32 s9, v12
	v_add_u32_e32 v12, s8, v36
	v_lshl_add_u64 v[6:7], v[18:19], 0, s[30:31]
	s_mov_b32 m0, s9
	v_readfirstlane_b32 s8, v12
	v_add_u32_e32 v12, s54, v33
	v_lshl_add_u64 v[6:7], v[24:25], 0, s[30:31]
	s_mov_b32 m0, s8
	v_readfirstlane_b32 s8, v12
	v_add_u32_e32 v12, s54, v34
	v_lshl_add_u64 v[6:7], v[26:27], 0, s[30:31]
	s_mov_b32 m0, s8
	v_readfirstlane_b32 s8, v12
	v_lshl_add_u64 v[6:7], v[28:29], 0, s[30:31]
	s_mov_b32 m0, s8
	s_add_i32 s8, 0, 0x8000
	v_lshl_add_u64 v[6:7], s[6:7], 0, v[8:9]
	v_lshl_add_u64 v[6:7], v[6:7], 0, v[10:11]
	v_lshl_add_u64 v[66:67], s[0:1], 0, v[6:7]
	v_lshl_add_u64 v[6:7], s[6:7], 0, v[2:3]
	v_lshl_add_u64 v[6:7], v[6:7], 0, v[4:5]
	v_lshl_add_u64 v[68:69], s[0:1], 0, v[6:7]
	v_lshl_add_u64 v[6:7], s[4:5], 0, v[20:21]
	v_lshl_add_u64 v[6:7], v[6:7], 0, v[22:23]
	v_lshl_add_u64 v[70:71], s[90:91], 0, v[6:7]
	v_lshl_add_u64 v[6:7], s[4:5], 0, v[14:15]
	v_lshl_add_u64 v[6:7], v[6:7], 0, v[16:17]
	v_lshl_add_u64 v[2:3], s[4:5], 0, v[2:3]
	v_lshl_add_u64 v[72:73], s[90:91], 0, v[6:7]
	v_lshl_add_u64 v[6:7], s[4:5], 0, v[8:9]
	v_lshl_add_u64 v[2:3], v[2:3], 0, v[4:5]
	v_lshl_add_u64 v[6:7], v[6:7], 0, v[10:11]
	v_lshl_add_u64 v[76:77], s[90:91], 0, v[2:3]
	v_mov_b32_e32 v2, 0
	v_add3_u32 v79, v31, s8, v32
	v_lshl_add_u64 v[74:75], s[90:91], 0, v[6:7]
	s_mov_b32 s6, 0
	s_mov_b64 s[4:5], 0
	v_mov_b32_e32 v3, v2
	v_mov_b32_e32 v4, v2
	v_mov_b32_e32 v5, v2
	v_mov_b32_e32 v6, v2
	v_mov_b32_e32 v7, v2
	v_mov_b32_e32 v8, v2
	v_mov_b32_e32 v9, v2
	v_mov_b32_e32 v10, v2
	v_mov_b32_e32 v11, v2
	v_mov_b32_e32 v12, v2
	v_mov_b32_e32 v13, v2
	v_mov_b32_e32 v14, v2
	v_mov_b32_e32 v15, v2
	v_mov_b32_e32 v16, v2
	v_mov_b32_e32 v17, v2
	v_mov_b32_e32 v18, v2
	v_mov_b32_e32 v19, v2
	v_mov_b32_e32 v20, v2
	v_mov_b32_e32 v21, v2
	v_mov_b32_e32 v22, v2
	v_mov_b32_e32 v23, v2
	v_mov_b32_e32 v24, v2
	v_mov_b32_e32 v25, v2
	v_mov_b32_e32 v26, v2
	v_mov_b32_e32 v27, v2
	v_mov_b32_e32 v28, v2
	v_mov_b32_e32 v29, v2
	v_mov_b32_e32 v30, v2
	v_mov_b32_e32 v31, v2
	v_mov_b32_e32 v32, v2
	v_mov_b32_e32 v33, v2
	v_mov_b32_e32 v34, v2
	v_mov_b32_e32 v35, v2
	v_mov_b32_e32 v36, v2
	v_mov_b32_e32 v37, v2
	v_mov_b32_e32 v38, v2
	v_mov_b32_e32 v39, v2
	v_mov_b32_e32 v40, v2
	v_mov_b32_e32 v41, v2
	v_mov_b32_e32 v42, v2
	v_mov_b32_e32 v43, v2
	v_mov_b32_e32 v44, v2
	v_mov_b32_e32 v45, v2
	v_mov_b32_e32 v46, v2
	v_mov_b32_e32 v47, v2
	v_mov_b32_e32 v48, v2
	v_mov_b32_e32 v49, v2
	v_mov_b32_e32 v50, v2
	v_mov_b32_e32 v51, v2
	v_mov_b32_e32 v52, v2
	v_mov_b32_e32 v53, v2
	v_mov_b32_e32 v54, v2
	v_mov_b32_e32 v55, v2
	v_mov_b32_e32 v56, v2
	v_mov_b32_e32 v57, v2
	v_mov_b32_e32 v58, v2
	v_mov_b32_e32 v59, v2
	v_mov_b32_e32 v60, v2
	v_mov_b32_e32 v61, v2
	v_mov_b32_e32 v62, v2
	v_mov_b32_e32 v63, v2
	v_mov_b32_e32 v64, v2
	v_mov_b32_e32 v65, v2
	v_readlane_b32 s3, v243, 3
	v_lshrrev_b32_e32 v141, 6, v142
	v_and_b32_e32 v139, 63, v142
	v_lshlrev_b32_e32 v141, 14, v141
	v_lshl_add_u32 v245, v139, 4, v141
	s_cmp_eq_u32 s3, 1
	s_cbranch_scc1 .Lgw_restore
	v_and_b32_e32 v141, 15, v142
	v_lshrrev_b32_e32 v139, 4, v142
	v_and_b32_e32 v139, 3, v139
	v_lshlrev_b32_e32 v140, 6, v141
	v_lshl_add_u32 v140, v139, 4, v140
	v_lshrrev_b32_e32 v139, 3, v141
	v_lshlrev_b32_e32 v139, 5, v139
	v_xor_b32_e32 v136, v140, v139
	v_lshrrev_b32_e32 v139, 7, v142
	v_lshl_add_u32 v135, v139, 12, v136
	v_lshrrev_b32_e32 v139, 6, v142
	v_and_b32_e32 v139, 1, v139
	v_lshl_add_u32 v136, v139, 12, v136
	v_add_u32_e32 v136, 0x4000, v136
	v_and_b32_e32 v141, 63, v142
	v_lshrrev_b32_e32 v139, 2, v141
	v_lshrrev_b32_e32 v140, 6, v142
	v_lshlrev_b32_e32 v139, 6, v139
	v_lshl_add_u32 v139, v140, 15, v139
	v_and_b32_e32 v140, 3, v141
	v_lshlrev_b32_e32 v140, 4, v140
	v_lshrrev_b32_e32 v141, 5, v141
	v_lshlrev_b32_e32 v141, 5, v141
	v_xor_b32_e32 v140, v140, v141
	v_add_u32_e32 v137, v139, v140
	v_add_u32_e32 v138, 0x40000, v137
	v_lshrrev_b32_e32 v141, 6, v142
	v_lshlrev_b32_e32 v141, 10, v141
	s_nop 0
	v_readfirstlane_b32 s20, v141
	s_lshl_b32 s38, s17, 19
	s_add_u32 s4, s24, s38
	s_addc_u32 s5, s25, 0
	s_lshl_b32 s38, s18, 18
	s_add_u32 s6, s14, s38
	s_addc_u32 s7, s15, 0
	s_cmp_eq_u32 s3, 2
	s_cbranch_scc1 .Lgw_single
	v_readlane_b32 s38, v243, 4
	s_lshl_b32 s38, s38, 18
	s_add_u32 s42, s14, s38
	s_addc_u32 s43, s15, 0
	v_mov_b32_e32 v62, 0
	v_mov_b32_e32 v63, 0
	v_mov_b32_e32 v64, 0
	v_mov_b32_e32 v65, 0
	v_mov_b32_e32 v58, 0
	v_mov_b32_e32 v59, 0
	v_mov_b32_e32 v60, 0
	v_mov_b32_e32 v61, 0
	v_mov_b32_e32 v54, 0
	v_mov_b32_e32 v55, 0
	v_mov_b32_e32 v56, 0
	v_mov_b32_e32 v57, 0
	v_mov_b32_e32 v50, 0
	v_mov_b32_e32 v51, 0
	v_mov_b32_e32 v52, 0
	v_mov_b32_e32 v53, 0
	v_mov_b32_e32 v46, 0
	v_mov_b32_e32 v47, 0
	v_mov_b32_e32 v48, 0
	v_mov_b32_e32 v49, 0
	v_mov_b32_e32 v42, 0
	v_mov_b32_e32 v43, 0
	v_mov_b32_e32 v44, 0
	v_mov_b32_e32 v45, 0
	v_mov_b32_e32 v38, 0
	v_mov_b32_e32 v39, 0
	v_mov_b32_e32 v40, 0
	v_mov_b32_e32 v41, 0
	v_mov_b32_e32 v34, 0
	v_mov_b32_e32 v35, 0
	v_mov_b32_e32 v36, 0
	v_mov_b32_e32 v37, 0
	v_mov_b32_e32 v30, 0
	v_mov_b32_e32 v31, 0
	v_mov_b32_e32 v32, 0
	v_mov_b32_e32 v33, 0
	v_mov_b32_e32 v26, 0
	v_mov_b32_e32 v27, 0
	v_mov_b32_e32 v28, 0
	v_mov_b32_e32 v29, 0
	v_mov_b32_e32 v22, 0
	v_mov_b32_e32 v23, 0
	v_mov_b32_e32 v24, 0
	v_mov_b32_e32 v25, 0
	v_mov_b32_e32 v18, 0
	v_mov_b32_e32 v19, 0
	v_mov_b32_e32 v20, 0
	v_mov_b32_e32 v21, 0
	v_mov_b32_e32 v14, 0
	v_mov_b32_e32 v15, 0
	v_mov_b32_e32 v16, 0
	v_mov_b32_e32 v17, 0
	v_mov_b32_e32 v10, 0
	v_mov_b32_e32 v11, 0
	v_mov_b32_e32 v12, 0
	v_mov_b32_e32 v13, 0
	v_mov_b32_e32 v6, 0
	v_mov_b32_e32 v7, 0
	v_mov_b32_e32 v8, 0
	v_mov_b32_e32 v9, 0
	v_mov_b32_e32 v2, 0
	v_mov_b32_e32 v3, 0
	v_mov_b32_e32 v4, 0
	v_mov_b32_e32 v5, 0
	v_mov_b32_e32 v66, 0
	v_mov_b32_e32 v67, 0
	v_mov_b32_e32 v68, 0
	v_mov_b32_e32 v69, 0
	v_mov_b32_e32 v70, 0
	v_mov_b32_e32 v71, 0
	v_mov_b32_e32 v72, 0
	v_mov_b32_e32 v73, 0
	v_mov_b32_e32 v74, 0
	v_mov_b32_e32 v75, 0
	v_mov_b32_e32 v76, 0
	v_mov_b32_e32 v77, 0
	v_mov_b32_e32 v78, 0
	v_mov_b32_e32 v79, 0
	v_mov_b32_e32 v80, 0
	v_mov_b32_e32 v81, 0
	v_mov_b32_e32 v82, 0
	v_mov_b32_e32 v83, 0
	v_mov_b32_e32 v84, 0
	v_mov_b32_e32 v85, 0
	v_mov_b32_e32 v86, 0
	v_mov_b32_e32 v87, 0
	v_mov_b32_e32 v88, 0
	v_mov_b32_e32 v89, 0
	v_mov_b32_e32 v90, 0
	v_mov_b32_e32 v91, 0
	v_mov_b32_e32 v92, 0
	v_mov_b32_e32 v93, 0
	v_mov_b32_e32 v94, 0
	v_mov_b32_e32 v95, 0
	v_mov_b32_e32 v96, 0
	v_mov_b32_e32 v97, 0
	v_mov_b32_e32 v98, 0
	v_mov_b32_e32 v99, 0
	v_mov_b32_e32 v100, 0
	v_mov_b32_e32 v101, 0
	v_mov_b32_e32 v102, 0
	v_mov_b32_e32 v103, 0
	v_mov_b32_e32 v104, 0
	v_mov_b32_e32 v105, 0
	v_mov_b32_e32 v106, 0
	v_mov_b32_e32 v107, 0
	v_mov_b32_e32 v108, 0
	v_mov_b32_e32 v109, 0
	v_mov_b32_e32 v110, 0
	v_mov_b32_e32 v111, 0
	v_mov_b32_e32 v112, 0
	v_mov_b32_e32 v113, 0
	v_mov_b32_e32 v114, 0
	v_mov_b32_e32 v115, 0
	v_mov_b32_e32 v116, 0
	v_mov_b32_e32 v117, 0
	v_mov_b32_e32 v118, 0
	v_mov_b32_e32 v119, 0
	v_mov_b32_e32 v120, 0
	v_mov_b32_e32 v121, 0
	v_mov_b32_e32 v122, 0
	v_mov_b32_e32 v123, 0
	v_mov_b32_e32 v124, 0
	v_mov_b32_e32 v125, 0
	v_mov_b32_e32 v126, 0
	v_mov_b32_e32 v127, 0
	v_mov_b32_e32 v128, 0
	v_mov_b32_e32 v129, 0
	s_add_u32 m0, s20, 0x0
	s_nop 0
	global_load_lds_dwordx4 v137, s[4:5]
	s_add_u32 m0, s20, 0x2000
	s_nop 0
	global_load_lds_dwordx4 v138, s[4:5]
	s_add_u32 m0, s20, 0x4000
	s_nop 0
	global_load_lds_dwordx4 v137, s[6:7]
	s_add_u32 m0, s20, 0x6000
	s_nop 0
	global_load_lds_dwordx4 v137, s[42:43]
	s_add_u32 s4, s4, 1024
	s_addc_u32 s5, s5, 0
	s_add_u32 s6, s6, 1024
	s_addc_u32 s7, s7, 0
	s_add_u32 s42, s42, 1024
	s_addc_u32 s43, s43, 0
	s_add_u32 m0, s20, 0x8000
	s_nop 0
	global_load_lds_dwordx4 v137, s[4:5]
	s_add_u32 m0, s20, 0xa000
	s_nop 0
	global_load_lds_dwordx4 v138, s[4:5]
	s_add_u32 m0, s20, 0xc000
	s_nop 0
	global_load_lds_dwordx4 v137, s[6:7]
	s_add_u32 m0, s20, 0xe000
	s_nop 0
	global_load_lds_dwordx4 v137, s[42:43]
	s_add_u32 s4, s4, 1024
	s_addc_u32 s5, s5, 0
	s_add_u32 s6, s6, 1024
	s_addc_u32 s7, s7, 0
	s_add_u32 s42, s42, 1024
	s_addc_u32 s43, s43, 0
	s_add_u32 m0, s20, 0x10000
	s_nop 0
	global_load_lds_dwordx4 v137, s[4:5]
	s_add_u32 m0, s20, 0x12000
	s_nop 0
	global_load_lds_dwordx4 v138, s[4:5]
	s_add_u32 m0, s20, 0x14000
	s_nop 0
	global_load_lds_dwordx4 v137, s[6:7]
	s_add_u32 m0, s20, 0x16000
	s_nop 0
	global_load_lds_dwordx4 v137, s[42:43]
	s_add_u32 s4, s4, 1024
	s_addc_u32 s5, s5, 0
	s_add_u32 s6, s6, 1024
	s_addc_u32 s7, s7, 0
	s_add_u32 s42, s42, 1024
	s_addc_u32 s43, s43, 0
.Lpk_gw_grpB1:
	v_mov_b32_e32 v178, 0
	v_mov_b32_e32 v179, 0
	v_mov_b32_e32 v180, 0
	v_mov_b32_e32 v181, 0
	v_mov_b32_e32 v182, 0
	v_mov_b32_e32 v183, 0
	v_mov_b32_e32 v184, 0
	v_mov_b32_e32 v185, 0
	v_mov_b32_e32 v186, 0
	v_mov_b32_e32 v187, 0
	v_mov_b32_e32 v188, 0
	v_mov_b32_e32 v189, 0
	v_mov_b32_e32 v190, 0
	v_mov_b32_e32 v191, 0
	v_mov_b32_e32 v192, 0
	v_mov_b32_e32 v193, 0
	v_mov_b32_e32 v218, 0
	v_mov_b32_e32 v219, 0
	v_mov_b32_e32 v220, 0
	v_mov_b32_e32 v221, 0
	v_mov_b32_e32 v222, 0
	v_mov_b32_e32 v223, 0
	v_mov_b32_e32 v224, 0
	v_mov_b32_e32 v225, 0
	v_mov_b32_e32 v226, 0
	v_mov_b32_e32 v227, 0
	v_mov_b32_e32 v228, 0
	v_mov_b32_e32 v229, 0
	v_mov_b32_e32 v230, 0
	v_mov_b32_e32 v231, 0
	v_mov_b32_e32 v232, 0
	v_mov_b32_e32 v233, 0
	s_mov_b32 s32, 7
.Lpk_gw_klB3:
	s_waitcnt vmcnt(8)
	s_barrier
	v_add_u32_e32 v139, 0x0, v135
	v_add_u32_e32 v140, 0x0, v136
	ds_read_b128 v[162:165], v139 offset:0
	ds_read_b128 v[166:169], v139 offset:1024
	ds_read_b128 v[170:173], v139 offset:2048
	ds_read_b128 v[174:177], v139 offset:3072
	ds_read_b128 v[194:197], v140 offset:0
	ds_read_b128 v[198:201], v140 offset:1024
	ds_read_b128 v[202:205], v140 offset:2048
	ds_read_b128 v[206:209], v140 offset:3072
	v_mfma_f32_16x16x32_bf16 v[66:69], v[218:221], v[178:181], v[66:69]
	v_mfma_f32_16x16x32_bf16 v[70:73], v[222:225], v[178:181], v[70:73]
	v_mfma_f32_16x16x32_bf16 v[74:77], v[226:229], v[178:181], v[74:77]
	s_add_u32 m0, s20, 0x18000
	s_nop 0
	global_load_lds_dwordx4 v137, s[4:5]
	v_mfma_f32_16x16x32_bf16 v[78:81], v[230:233], v[178:181], v[78:81]
	v_mfma_f32_16x16x32_bf16 v[82:85], v[218:221], v[182:185], v[82:85]
	v_mfma_f32_16x16x32_bf16 v[86:89], v[222:225], v[182:185], v[86:89]
	v_mfma_f32_16x16x32_bf16 v[90:93], v[226:229], v[182:185], v[90:93]
	s_add_u32 m0, s20, 0x1a000
	s_nop 0
	global_load_lds_dwordx4 v138, s[4:5]
	v_mfma_f32_16x16x32_bf16 v[94:97], v[230:233], v[182:185], v[94:97]
	v_mfma_f32_16x16x32_bf16 v[98:101], v[218:221], v[186:189], v[98:101]
	v_mfma_f32_16x16x32_bf16 v[102:105], v[222:225], v[186:189], v[102:105]
	v_mfma_f32_16x16x32_bf16 v[106:109], v[226:229], v[186:189], v[106:109]
	s_add_u32 m0, s20, 0x1c000
	s_nop 0
	global_load_lds_dwordx4 v137, s[6:7]
	v_mfma_f32_16x16x32_bf16 v[110:113], v[230:233], v[186:189], v[110:113]
	v_mfma_f32_16x16x32_bf16 v[114:117], v[218:221], v[190:193], v[114:117]
	v_mfma_f32_16x16x32_bf16 v[118:121], v[222:225], v[190:193], v[118:121]
	v_mfma_f32_16x16x32_bf16 v[122:125], v[226:229], v[190:193], v[122:125]
	s_add_u32 m0, s20, 0x1e000
	s_nop 0
	global_load_lds_dwordx4 v137, s[42:43]
	v_mfma_f32_16x16x32_bf16 v[126:129], v[230:233], v[190:193], v[126:129]
	s_add_u32 s4, s4, 1024
	s_addc_u32 s5, s5, 0
	s_add_u32 s6, s6, 1024
	s_addc_u32 s7, s7, 0
	s_add_u32 s42, s42, 1024
	s_addc_u32 s43, s43, 0
	ds_read_b128 v[218:221], v140 offset:8192
	ds_read_b128 v[222:225], v140 offset:9216
	ds_read_b128 v[226:229], v140 offset:10240
	ds_read_b128 v[230:233], v140 offset:11264
	s_waitcnt lgkmcnt(4)
	v_mfma_f32_16x16x32_bf16 v[62:65], v[194:197], v[162:165], v[62:65]
	v_mfma_f32_16x16x32_bf16 v[58:61], v[198:201], v[162:165], v[58:61]
	v_mfma_f32_16x16x32_bf16 v[54:57], v[202:205], v[162:165], v[54:57]
	v_mfma_f32_16x16x32_bf16 v[50:53], v[206:209], v[162:165], v[50:53]
	v_mfma_f32_16x16x32_bf16 v[46:49], v[194:197], v[166:169], v[46:49]
	v_mfma_f32_16x16x32_bf16 v[42:45], v[198:201], v[166:169], v[42:45]
	v_mfma_f32_16x16x32_bf16 v[38:41], v[202:205], v[166:169], v[38:41]
	v_mfma_f32_16x16x32_bf16 v[34:37], v[206:209], v[166:169], v[34:37]
	v_mfma_f32_16x16x32_bf16 v[30:33], v[194:197], v[170:173], v[30:33]
	v_mfma_f32_16x16x32_bf16 v[26:29], v[198:201], v[170:173], v[26:29]
	v_mfma_f32_16x16x32_bf16 v[22:25], v[202:205], v[170:173], v[22:25]
	v_mfma_f32_16x16x32_bf16 v[18:21], v[206:209], v[170:173], v[18:21]
	v_mfma_f32_16x16x32_bf16 v[14:17], v[194:197], v[174:177], v[14:17]
	v_mfma_f32_16x16x32_bf16 v[10:13], v[198:201], v[174:177], v[10:13]
	v_mfma_f32_16x16x32_bf16 v[6:9], v[202:205], v[174:177], v[6:9]
	v_mfma_f32_16x16x32_bf16 v[2:5], v[206:209], v[174:177], v[2:5]
	s_waitcnt lgkmcnt(0)
	s_waitcnt vmcnt(8)
	s_barrier
	v_add_u32_e32 v139, 0x8000, v135
	v_add_u32_e32 v140, 0x8000, v136
	ds_read_b128 v[178:181], v139 offset:0
	ds_read_b128 v[182:185], v139 offset:1024
	ds_read_b128 v[186:189], v139 offset:2048
	ds_read_b128 v[190:193], v139 offset:3072
	ds_read_b128 v[194:197], v140 offset:0
	ds_read_b128 v[198:201], v140 offset:1024
	ds_read_b128 v[202:205], v140 offset:2048
	ds_read_b128 v[206:209], v140 offset:3072
	v_mfma_f32_16x16x32_bf16 v[66:69], v[218:221], v[162:165], v[66:69]
	v_mfma_f32_16x16x32_bf16 v[70:73], v[222:225], v[162:165], v[70:73]
	v_mfma_f32_16x16x32_bf16 v[74:77], v[226:229], v[162:165], v[74:77]
	s_add_u32 m0, s20, 0x0
	s_nop 0
	global_load_lds_dwordx4 v137, s[4:5]
	v_mfma_f32_16x16x32_bf16 v[78:81], v[230:233], v[162:165], v[78:81]
	v_mfma_f32_16x16x32_bf16 v[82:85], v[218:221], v[166:169], v[82:85]
	v_mfma_f32_16x16x32_bf16 v[86:89], v[222:225], v[166:169], v[86:89]
	v_mfma_f32_16x16x32_bf16 v[90:93], v[226:229], v[166:169], v[90:93]
	s_add_u32 m0, s20, 0x2000
	s_nop 0
	global_load_lds_dwordx4 v138, s[4:5]
	v_mfma_f32_16x16x32_bf16 v[94:97], v[230:233], v[166:169], v[94:97]
	v_mfma_f32_16x16x32_bf16 v[98:101], v[218:221], v[170:173], v[98:101]
	v_mfma_f32_16x16x32_bf16 v[102:105], v[222:225], v[170:173], v[102:105]
	v_mfma_f32_16x16x32_bf16 v[106:109], v[226:229], v[170:173], v[106:109]
	s_add_u32 m0, s20, 0x4000
	s_nop 0
	global_load_lds_dwordx4 v137, s[6:7]
	v_mfma_f32_16x16x32_bf16 v[110:113], v[230:233], v[170:173], v[110:113]
	v_mfma_f32_16x16x32_bf16 v[114:117], v[218:221], v[174:177], v[114:117]
	v_mfma_f32_16x16x32_bf16 v[118:121], v[222:225], v[174:177], v[118:121]
	v_mfma_f32_16x16x32_bf16 v[122:125], v[226:229], v[174:177], v[122:125]
	s_add_u32 m0, s20, 0x6000
	s_nop 0
	global_load_lds_dwordx4 v137, s[42:43]
	v_mfma_f32_16x16x32_bf16 v[126:129], v[230:233], v[174:177], v[126:129]
	s_add_u32 s4, s4, 1024
	s_addc_u32 s5, s5, 0
	s_add_u32 s6, s6, 1024
	s_addc_u32 s7, s7, 0
	s_add_u32 s42, s42, 1024
	s_addc_u32 s43, s43, 0
	ds_read_b128 v[218:221], v140 offset:8192
	ds_read_b128 v[222:225], v140 offset:9216
	ds_read_b128 v[226:229], v140 offset:10240
	ds_read_b128 v[230:233], v140 offset:11264
	s_waitcnt lgkmcnt(4)
	v_mfma_f32_16x16x32_bf16 v[62:65], v[194:197], v[178:181], v[62:65]
	v_mfma_f32_16x16x32_bf16 v[58:61], v[198:201], v[178:181], v[58:61]
	v_mfma_f32_16x16x32_bf16 v[54:57], v[202:205], v[178:181], v[54:57]
	v_mfma_f32_16x16x32_bf16 v[50:53], v[206:209], v[178:181], v[50:53]
	v_mfma_f32_16x16x32_bf16 v[46:49], v[194:197], v[182:185], v[46:49]
	v_mfma_f32_16x16x32_bf16 v[42:45], v[198:201], v[182:185], v[42:45]
	v_mfma_f32_16x16x32_bf16 v[38:41], v[202:205], v[182:185], v[38:41]
	v_mfma_f32_16x16x32_bf16 v[34:37], v[206:209], v[182:185], v[34:37]
	v_mfma_f32_16x16x32_bf16 v[30:33], v[194:197], v[186:189], v[30:33]
	v_mfma_f32_16x16x32_bf16 v[26:29], v[198:201], v[186:189], v[26:29]
	v_mfma_f32_16x16x32_bf16 v[22:25], v[202:205], v[186:189], v[22:25]
	v_mfma_f32_16x16x32_bf16 v[18:21], v[206:209], v[186:189], v[18:21]
	v_mfma_f32_16x16x32_bf16 v[14:17], v[194:197], v[190:193], v[14:17]
	v_mfma_f32_16x16x32_bf16 v[10:13], v[198:201], v[190:193], v[10:13]
	v_mfma_f32_16x16x32_bf16 v[6:9], v[202:205], v[190:193], v[6:9]
	v_mfma_f32_16x16x32_bf16 v[2:5], v[206:209], v[190:193], v[2:5]
	s_waitcnt lgkmcnt(0)
	s_waitcnt vmcnt(8)
	s_barrier
	v_add_u32_e32 v139, 0x10000, v135
	v_add_u32_e32 v140, 0x10000, v136
	ds_read_b128 v[162:165], v139 offset:0
	ds_read_b128 v[166:169], v139 offset:1024
	ds_read_b128 v[170:173], v139 offset:2048
	ds_read_b128 v[174:177], v139 offset:3072
	ds_read_b128 v[194:197], v140 offset:0
	ds_read_b128 v[198:201], v140 offset:1024
	ds_read_b128 v[202:205], v140 offset:2048
	ds_read_b128 v[206:209], v140 offset:3072
	v_mfma_f32_16x16x32_bf16 v[66:69], v[218:221], v[178:181], v[66:69]
	v_mfma_f32_16x16x32_bf16 v[70:73], v[222:225], v[178:181], v[70:73]
	v_mfma_f32_16x16x32_bf16 v[74:77], v[226:229], v[178:181], v[74:77]
	s_add_u32 m0, s20, 0x8000
	s_nop 0
	global_load_lds_dwordx4 v137, s[4:5]
	v_mfma_f32_16x16x32_bf16 v[78:81], v[230:233], v[178:181], v[78:81]
	v_mfma_f32_16x16x32_bf16 v[82:85], v[218:221], v[182:185], v[82:85]
	v_mfma_f32_16x16x32_bf16 v[86:89], v[222:225], v[182:185], v[86:89]
	v_mfma_f32_16x16x32_bf16 v[90:93], v[226:229], v[182:185], v[90:93]
	s_add_u32 m0, s20, 0xa000
	s_nop 0
	global_load_lds_dwordx4 v138, s[4:5]
	v_mfma_f32_16x16x32_bf16 v[94:97], v[230:233], v[182:185], v[94:97]
	v_mfma_f32_16x16x32_bf16 v[98:101], v[218:221], v[186:189], v[98:101]
	v_mfma_f32_16x16x32_bf16 v[102:105], v[222:225], v[186:189], v[102:105]
	v_mfma_f32_16x16x32_bf16 v[106:109], v[226:229], v[186:189], v[106:109]
	s_add_u32 m0, s20, 0xc000
	s_nop 0
	global_load_lds_dwordx4 v137, s[6:7]
	v_mfma_f32_16x16x32_bf16 v[110:113], v[230:233], v[186:189], v[110:113]
	v_mfma_f32_16x16x32_bf16 v[114:117], v[218:221], v[190:193], v[114:117]
	v_mfma_f32_16x16x32_bf16 v[118:121], v[222:225], v[190:193], v[118:121]
	v_mfma_f32_16x16x32_bf16 v[122:125], v[226:229], v[190:193], v[122:125]
	s_add_u32 m0, s20, 0xe000
	s_nop 0
	global_load_lds_dwordx4 v137, s[42:43]
	v_mfma_f32_16x16x32_bf16 v[126:129], v[230:233], v[190:193], v[126:129]
	s_add_u32 s4, s4, 1024
	s_addc_u32 s5, s5, 0
	s_add_u32 s6, s6, 1024
	s_addc_u32 s7, s7, 0
	s_add_u32 s42, s42, 1024
	s_addc_u32 s43, s43, 0
	ds_read_b128 v[218:221], v140 offset:8192
	ds_read_b128 v[222:225], v140 offset:9216
	ds_read_b128 v[226:229], v140 offset:10240
	ds_read_b128 v[230:233], v140 offset:11264
	s_waitcnt lgkmcnt(4)
	v_mfma_f32_16x16x32_bf16 v[62:65], v[194:197], v[162:165], v[62:65]
	v_mfma_f32_16x16x32_bf16 v[58:61], v[198:201], v[162:165], v[58:61]
	v_mfma_f32_16x16x32_bf16 v[54:57], v[202:205], v[162:165], v[54:57]
	v_mfma_f32_16x16x32_bf16 v[50:53], v[206:209], v[162:165], v[50:53]
	v_mfma_f32_16x16x32_bf16 v[46:49], v[194:197], v[166:169], v[46:49]
	v_mfma_f32_16x16x32_bf16 v[42:45], v[198:201], v[166:169], v[42:45]
	v_mfma_f32_16x16x32_bf16 v[38:41], v[202:205], v[166:169], v[38:41]
	v_mfma_f32_16x16x32_bf16 v[34:37], v[206:209], v[166:169], v[34:37]
	v_mfma_f32_16x16x32_bf16 v[30:33], v[194:197], v[170:173], v[30:33]
	v_mfma_f32_16x16x32_bf16 v[26:29], v[198:201], v[170:173], v[26:29]
	v_mfma_f32_16x16x32_bf16 v[22:25], v[202:205], v[170:173], v[22:25]
	v_mfma_f32_16x16x32_bf16 v[18:21], v[206:209], v[170:173], v[18:21]
	v_mfma_f32_16x16x32_bf16 v[14:17], v[194:197], v[174:177], v[14:17]
	v_mfma_f32_16x16x32_bf16 v[10:13], v[198:201], v[174:177], v[10:13]
	v_mfma_f32_16x16x32_bf16 v[6:9], v[202:205], v[174:177], v[6:9]
	v_mfma_f32_16x16x32_bf16 v[2:5], v[206:209], v[174:177], v[2:5]
	s_waitcnt lgkmcnt(0)
	s_waitcnt vmcnt(8)
	s_barrier
	v_add_u32_e32 v139, 0x18000, v135
	v_add_u32_e32 v140, 0x18000, v136
	ds_read_b128 v[178:181], v139 offset:0
	ds_read_b128 v[182:185], v139 offset:1024
	ds_read_b128 v[186:189], v139 offset:2048
	ds_read_b128 v[190:193], v139 offset:3072
	ds_read_b128 v[194:197], v140 offset:0
	ds_read_b128 v[198:201], v140 offset:1024
	ds_read_b128 v[202:205], v140 offset:2048
	ds_read_b128 v[206:209], v140 offset:3072
	v_mfma_f32_16x16x32_bf16 v[66:69], v[218:221], v[162:165], v[66:69]
	v_mfma_f32_16x16x32_bf16 v[70:73], v[222:225], v[162:165], v[70:73]
	v_mfma_f32_16x16x32_bf16 v[74:77], v[226:229], v[162:165], v[74:77]
	s_add_u32 m0, s20, 0x10000
	s_nop 0
	global_load_lds_dwordx4 v137, s[4:5]
	v_mfma_f32_16x16x32_bf16 v[78:81], v[230:233], v[162:165], v[78:81]
	v_mfma_f32_16x16x32_bf16 v[82:85], v[218:221], v[166:169], v[82:85]
	v_mfma_f32_16x16x32_bf16 v[86:89], v[222:225], v[166:169], v[86:89]
	v_mfma_f32_16x16x32_bf16 v[90:93], v[226:229], v[166:169], v[90:93]
	s_add_u32 m0, s20, 0x12000
	s_nop 0
	global_load_lds_dwordx4 v138, s[4:5]
	v_mfma_f32_16x16x32_bf16 v[94:97], v[230:233], v[166:169], v[94:97]
	v_mfma_f32_16x16x32_bf16 v[98:101], v[218:221], v[170:173], v[98:101]
	v_mfma_f32_16x16x32_bf16 v[102:105], v[222:225], v[170:173], v[102:105]
	v_mfma_f32_16x16x32_bf16 v[106:109], v[226:229], v[170:173], v[106:109]
	s_add_u32 m0, s20, 0x14000
	s_nop 0
	global_load_lds_dwordx4 v137, s[6:7]
	v_mfma_f32_16x16x32_bf16 v[110:113], v[230:233], v[170:173], v[110:113]
	v_mfma_f32_16x16x32_bf16 v[114:117], v[218:221], v[174:177], v[114:117]
	v_mfma_f32_16x16x32_bf16 v[118:121], v[222:225], v[174:177], v[118:121]
	v_mfma_f32_16x16x32_bf16 v[122:125], v[226:229], v[174:177], v[122:125]
	s_add_u32 m0, s20, 0x16000
	s_nop 0
	global_load_lds_dwordx4 v137, s[42:43]
	v_mfma_f32_16x16x32_bf16 v[126:129], v[230:233], v[174:177], v[126:129]
	s_add_u32 s4, s4, 1024
	s_addc_u32 s5, s5, 0
	s_add_u32 s6, s6, 1024
	s_addc_u32 s7, s7, 0
	s_add_u32 s42, s42, 1024
	s_addc_u32 s43, s43, 0
	ds_read_b128 v[218:221], v140 offset:8192
	ds_read_b128 v[222:225], v140 offset:9216
	ds_read_b128 v[226:229], v140 offset:10240
	ds_read_b128 v[230:233], v140 offset:11264
	s_waitcnt lgkmcnt(4)
	v_mfma_f32_16x16x32_bf16 v[62:65], v[194:197], v[178:181], v[62:65]
	v_mfma_f32_16x16x32_bf16 v[58:61], v[198:201], v[178:181], v[58:61]
	v_mfma_f32_16x16x32_bf16 v[54:57], v[202:205], v[178:181], v[54:57]
	v_mfma_f32_16x16x32_bf16 v[50:53], v[206:209], v[178:181], v[50:53]
	v_mfma_f32_16x16x32_bf16 v[46:49], v[194:197], v[182:185], v[46:49]
	v_mfma_f32_16x16x32_bf16 v[42:45], v[198:201], v[182:185], v[42:45]
	v_mfma_f32_16x16x32_bf16 v[38:41], v[202:205], v[182:185], v[38:41]
	v_mfma_f32_16x16x32_bf16 v[34:37], v[206:209], v[182:185], v[34:37]
	v_mfma_f32_16x16x32_bf16 v[30:33], v[194:197], v[186:189], v[30:33]
	v_mfma_f32_16x16x32_bf16 v[26:29], v[198:201], v[186:189], v[26:29]
	v_mfma_f32_16x16x32_bf16 v[22:25], v[202:205], v[186:189], v[22:25]
	v_mfma_f32_16x16x32_bf16 v[18:21], v[206:209], v[186:189], v[18:21]
	v_mfma_f32_16x16x32_bf16 v[14:17], v[194:197], v[190:193], v[14:17]
	v_mfma_f32_16x16x32_bf16 v[10:13], v[198:201], v[190:193], v[10:13]
	v_mfma_f32_16x16x32_bf16 v[6:9], v[202:205], v[190:193], v[6:9]
	v_mfma_f32_16x16x32_bf16 v[2:5], v[206:209], v[190:193], v[2:5]
	s_waitcnt lgkmcnt(0)
	s_sub_u32 s32, s32, 1
	s_cmp_lg_u32 s32, 0
	s_cbranch_scc1 .Lpk_gw_klB3
	s_waitcnt vmcnt(8)
	s_barrier
	v_add_u32_e32 v139, 0x0, v135
	v_add_u32_e32 v140, 0x0, v136
	ds_read_b128 v[162:165], v139 offset:0
	ds_read_b128 v[166:169], v139 offset:1024
	ds_read_b128 v[170:173], v139 offset:2048
	ds_read_b128 v[174:177], v139 offset:3072
	ds_read_b128 v[194:197], v140 offset:0
	ds_read_b128 v[198:201], v140 offset:1024
	ds_read_b128 v[202:205], v140 offset:2048
	ds_read_b128 v[206:209], v140 offset:3072
	v_mfma_f32_16x16x32_bf16 v[66:69], v[218:221], v[178:181], v[66:69]
	v_mfma_f32_16x16x32_bf16 v[70:73], v[222:225], v[178:181], v[70:73]
	v_mfma_f32_16x16x32_bf16 v[74:77], v[226:229], v[178:181], v[74:77]
	s_add_u32 m0, s20, 0x18000
	s_nop 0
	global_load_lds_dwordx4 v137, s[4:5]
	v_mfma_f32_16x16x32_bf16 v[78:81], v[230:233], v[178:181], v[78:81]
	v_mfma_f32_16x16x32_bf16 v[82:85], v[218:221], v[182:185], v[82:85]
	v_mfma_f32_16x16x32_bf16 v[86:89], v[222:225], v[182:185], v[86:89]
	v_mfma_f32_16x16x32_bf16 v[90:93], v[226:229], v[182:185], v[90:93]
	s_add_u32 m0, s20, 0x1a000
	s_nop 0
	global_load_lds_dwordx4 v138, s[4:5]
	v_mfma_f32_16x16x32_bf16 v[94:97], v[230:233], v[182:185], v[94:97]
	v_mfma_f32_16x16x32_bf16 v[98:101], v[218:221], v[186:189], v[98:101]
	v_mfma_f32_16x16x32_bf16 v[102:105], v[222:225], v[186:189], v[102:105]
	v_mfma_f32_16x16x32_bf16 v[106:109], v[226:229], v[186:189], v[106:109]
	s_add_u32 m0, s20, 0x1c000
	s_nop 0
	global_load_lds_dwordx4 v137, s[6:7]
	v_mfma_f32_16x16x32_bf16 v[110:113], v[230:233], v[186:189], v[110:113]
	v_mfma_f32_16x16x32_bf16 v[114:117], v[218:221], v[190:193], v[114:117]
	v_mfma_f32_16x16x32_bf16 v[118:121], v[222:225], v[190:193], v[118:121]
	v_mfma_f32_16x16x32_bf16 v[122:125], v[226:229], v[190:193], v[122:125]
	s_add_u32 m0, s20, 0x1e000
	s_nop 0
	global_load_lds_dwordx4 v137, s[42:43]
	v_mfma_f32_16x16x32_bf16 v[126:129], v[230:233], v[190:193], v[126:129]
	s_add_u32 s4, s4, 1024
	s_addc_u32 s5, s5, 0
	s_add_u32 s6, s6, 1024
	s_addc_u32 s7, s7, 0
	s_add_u32 s42, s42, 1024
	s_addc_u32 s43, s43, 0
	ds_read_b128 v[218:221], v140 offset:8192
	ds_read_b128 v[222:225], v140 offset:9216
	ds_read_b128 v[226:229], v140 offset:10240
	ds_read_b128 v[230:233], v140 offset:11264
	s_waitcnt lgkmcnt(4)
	v_mfma_f32_16x16x32_bf16 v[62:65], v[194:197], v[162:165], v[62:65]
	v_mfma_f32_16x16x32_bf16 v[58:61], v[198:201], v[162:165], v[58:61]
	v_mfma_f32_16x16x32_bf16 v[54:57], v[202:205], v[162:165], v[54:57]
	v_mfma_f32_16x16x32_bf16 v[50:53], v[206:209], v[162:165], v[50:53]
	v_mfma_f32_16x16x32_bf16 v[46:49], v[194:197], v[166:169], v[46:49]
	v_mfma_f32_16x16x32_bf16 v[42:45], v[198:201], v[166:169], v[42:45]
	v_mfma_f32_16x16x32_bf16 v[38:41], v[202:205], v[166:169], v[38:41]
	v_mfma_f32_16x16x32_bf16 v[34:37], v[206:209], v[166:169], v[34:37]
	v_mfma_f32_16x16x32_bf16 v[30:33], v[194:197], v[170:173], v[30:33]
	v_mfma_f32_16x16x32_bf16 v[26:29], v[198:201], v[170:173], v[26:29]
	v_mfma_f32_16x16x32_bf16 v[22:25], v[202:205], v[170:173], v[22:25]
	v_mfma_f32_16x16x32_bf16 v[18:21], v[206:209], v[170:173], v[18:21]
	v_mfma_f32_16x16x32_bf16 v[14:17], v[194:197], v[174:177], v[14:17]
	v_mfma_f32_16x16x32_bf16 v[10:13], v[198:201], v[174:177], v[10:13]
	v_mfma_f32_16x16x32_bf16 v[6:9], v[202:205], v[174:177], v[6:9]
	v_mfma_f32_16x16x32_bf16 v[2:5], v[206:209], v[174:177], v[2:5]
	s_waitcnt lgkmcnt(0)
	s_waitcnt vmcnt(8)
	s_barrier
	v_add_u32_e32 v139, 0x8000, v135
	v_add_u32_e32 v140, 0x8000, v136
	ds_read_b128 v[178:181], v139 offset:0
	ds_read_b128 v[182:185], v139 offset:1024
	ds_read_b128 v[186:189], v139 offset:2048
	ds_read_b128 v[190:193], v139 offset:3072
	ds_read_b128 v[194:197], v140 offset:0
	ds_read_b128 v[198:201], v140 offset:1024
	ds_read_b128 v[202:205], v140 offset:2048
	ds_read_b128 v[206:209], v140 offset:3072
	v_mfma_f32_16x16x32_bf16 v[66:69], v[218:221], v[162:165], v[66:69]
	v_mfma_f32_16x16x32_bf16 v[70:73], v[222:225], v[162:165], v[70:73]
	v_mfma_f32_16x16x32_bf16 v[74:77], v[226:229], v[162:165], v[74:77]
	v_mfma_f32_16x16x32_bf16 v[78:81], v[230:233], v[162:165], v[78:81]
	v_mfma_f32_16x16x32_bf16 v[82:85], v[218:221], v[166:169], v[82:85]
	v_mfma_f32_16x16x32_bf16 v[86:89], v[222:225], v[166:169], v[86:89]
	v_mfma_f32_16x16x32_bf16 v[90:93], v[226:229], v[166:169], v[90:93]
	v_mfma_f32_16x16x32_bf16 v[94:97], v[230:233], v[166:169], v[94:97]
	v_mfma_f32_16x16x32_bf16 v[98:101], v[218:221], v[170:173], v[98:101]
	v_mfma_f32_16x16x32_bf16 v[102:105], v[222:225], v[170:173], v[102:105]
	v_mfma_f32_16x16x32_bf16 v[106:109], v[226:229], v[170:173], v[106:109]
	v_mfma_f32_16x16x32_bf16 v[110:113], v[230:233], v[170:173], v[110:113]
	v_mfma_f32_16x16x32_bf16 v[114:117], v[218:221], v[174:177], v[114:117]
	v_mfma_f32_16x16x32_bf16 v[118:121], v[222:225], v[174:177], v[118:121]
	v_mfma_f32_16x16x32_bf16 v[122:125], v[226:229], v[174:177], v[122:125]
	v_mfma_f32_16x16x32_bf16 v[126:129], v[230:233], v[174:177], v[126:129]
	ds_read_b128 v[218:221], v140 offset:8192
	ds_read_b128 v[222:225], v140 offset:9216
	ds_read_b128 v[226:229], v140 offset:10240
	ds_read_b128 v[230:233], v140 offset:11264
	s_waitcnt lgkmcnt(4)
	v_mfma_f32_16x16x32_bf16 v[62:65], v[194:197], v[178:181], v[62:65]
	v_mfma_f32_16x16x32_bf16 v[58:61], v[198:201], v[178:181], v[58:61]
	v_mfma_f32_16x16x32_bf16 v[54:57], v[202:205], v[178:181], v[54:57]
	v_mfma_f32_16x16x32_bf16 v[50:53], v[206:209], v[178:181], v[50:53]
	v_mfma_f32_16x16x32_bf16 v[46:49], v[194:197], v[182:185], v[46:49]
	v_mfma_f32_16x16x32_bf16 v[42:45], v[198:201], v[182:185], v[42:45]
	v_mfma_f32_16x16x32_bf16 v[38:41], v[202:205], v[182:185], v[38:41]
	v_mfma_f32_16x16x32_bf16 v[34:37], v[206:209], v[182:185], v[34:37]
	v_mfma_f32_16x16x32_bf16 v[30:33], v[194:197], v[186:189], v[30:33]
	v_mfma_f32_16x16x32_bf16 v[26:29], v[198:201], v[186:189], v[26:29]
	v_mfma_f32_16x16x32_bf16 v[22:25], v[202:205], v[186:189], v[22:25]
	v_mfma_f32_16x16x32_bf16 v[18:21], v[206:209], v[186:189], v[18:21]
	v_mfma_f32_16x16x32_bf16 v[14:17], v[194:197], v[190:193], v[14:17]
	v_mfma_f32_16x16x32_bf16 v[10:13], v[198:201], v[190:193], v[10:13]
	v_mfma_f32_16x16x32_bf16 v[6:9], v[202:205], v[190:193], v[6:9]
	v_mfma_f32_16x16x32_bf16 v[2:5], v[206:209], v[190:193], v[2:5]
	s_waitcnt lgkmcnt(0)
	s_waitcnt vmcnt(4)
	s_barrier
	v_add_u32_e32 v139, 0x10000, v135
	v_add_u32_e32 v140, 0x10000, v136
	ds_read_b128 v[162:165], v139 offset:0
	ds_read_b128 v[166:169], v139 offset:1024
	ds_read_b128 v[170:173], v139 offset:2048
	ds_read_b128 v[174:177], v139 offset:3072
	ds_read_b128 v[194:197], v140 offset:0
	ds_read_b128 v[198:201], v140 offset:1024
	ds_read_b128 v[202:205], v140 offset:2048
	ds_read_b128 v[206:209], v140 offset:3072
	v_mfma_f32_16x16x32_bf16 v[66:69], v[218:221], v[178:181], v[66:69]
	v_mfma_f32_16x16x32_bf16 v[70:73], v[222:225], v[178:181], v[70:73]
	v_mfma_f32_16x16x32_bf16 v[74:77], v[226:229], v[178:181], v[74:77]
	v_mfma_f32_16x16x32_bf16 v[78:81], v[230:233], v[178:181], v[78:81]
	v_mfma_f32_16x16x32_bf16 v[82:85], v[218:221], v[182:185], v[82:85]
	v_mfma_f32_16x16x32_bf16 v[86:89], v[222:225], v[182:185], v[86:89]
	v_mfma_f32_16x16x32_bf16 v[90:93], v[226:229], v[182:185], v[90:93]
	v_mfma_f32_16x16x32_bf16 v[94:97], v[230:233], v[182:185], v[94:97]
	v_mfma_f32_16x16x32_bf16 v[98:101], v[218:221], v[186:189], v[98:101]
	v_mfma_f32_16x16x32_bf16 v[102:105], v[222:225], v[186:189], v[102:105]
	v_mfma_f32_16x16x32_bf16 v[106:109], v[226:229], v[186:189], v[106:109]
	v_mfma_f32_16x16x32_bf16 v[110:113], v[230:233], v[186:189], v[110:113]
	v_mfma_f32_16x16x32_bf16 v[114:117], v[218:221], v[190:193], v[114:117]
	v_mfma_f32_16x16x32_bf16 v[118:121], v[222:225], v[190:193], v[118:121]
	v_mfma_f32_16x16x32_bf16 v[122:125], v[226:229], v[190:193], v[122:125]
	v_mfma_f32_16x16x32_bf16 v[126:129], v[230:233], v[190:193], v[126:129]
	ds_read_b128 v[218:221], v140 offset:8192
	ds_read_b128 v[222:225], v140 offset:9216
	ds_read_b128 v[226:229], v140 offset:10240
	ds_read_b128 v[230:233], v140 offset:11264
	s_waitcnt lgkmcnt(4)
	v_mfma_f32_16x16x32_bf16 v[62:65], v[194:197], v[162:165], v[62:65]
	v_mfma_f32_16x16x32_bf16 v[58:61], v[198:201], v[162:165], v[58:61]
	v_mfma_f32_16x16x32_bf16 v[54:57], v[202:205], v[162:165], v[54:57]
	v_mfma_f32_16x16x32_bf16 v[50:53], v[206:209], v[162:165], v[50:53]
	v_mfma_f32_16x16x32_bf16 v[46:49], v[194:197], v[166:169], v[46:49]
	v_mfma_f32_16x16x32_bf16 v[42:45], v[198:201], v[166:169], v[42:45]
	v_mfma_f32_16x16x32_bf16 v[38:41], v[202:205], v[166:169], v[38:41]
	v_mfma_f32_16x16x32_bf16 v[34:37], v[206:209], v[166:169], v[34:37]
	v_mfma_f32_16x16x32_bf16 v[30:33], v[194:197], v[170:173], v[30:33]
	v_mfma_f32_16x16x32_bf16 v[26:29], v[198:201], v[170:173], v[26:29]
	v_mfma_f32_16x16x32_bf16 v[22:25], v[202:205], v[170:173], v[22:25]
	v_mfma_f32_16x16x32_bf16 v[18:21], v[206:209], v[170:173], v[18:21]
	v_mfma_f32_16x16x32_bf16 v[14:17], v[194:197], v[174:177], v[14:17]
	v_mfma_f32_16x16x32_bf16 v[10:13], v[198:201], v[174:177], v[10:13]
	v_mfma_f32_16x16x32_bf16 v[6:9], v[202:205], v[174:177], v[6:9]
	v_mfma_f32_16x16x32_bf16 v[2:5], v[206:209], v[174:177], v[2:5]
	s_waitcnt lgkmcnt(0)
	s_waitcnt vmcnt(0)
	s_barrier
	v_add_u32_e32 v139, 0x18000, v135
	v_add_u32_e32 v140, 0x18000, v136
	ds_read_b128 v[178:181], v139 offset:0
	ds_read_b128 v[182:185], v139 offset:1024
	ds_read_b128 v[186:189], v139 offset:2048
	ds_read_b128 v[190:193], v139 offset:3072
	ds_read_b128 v[194:197], v140 offset:0
	ds_read_b128 v[198:201], v140 offset:1024
	ds_read_b128 v[202:205], v140 offset:2048
	ds_read_b128 v[206:209], v140 offset:3072
	v_mfma_f32_16x16x32_bf16 v[66:69], v[218:221], v[162:165], v[66:69]
	v_mfma_f32_16x16x32_bf16 v[70:73], v[222:225], v[162:165], v[70:73]
	v_mfma_f32_16x16x32_bf16 v[74:77], v[226:229], v[162:165], v[74:77]
	v_mfma_f32_16x16x32_bf16 v[78:81], v[230:233], v[162:165], v[78:81]
	v_mfma_f32_16x16x32_bf16 v[82:85], v[218:221], v[166:169], v[82:85]
	v_mfma_f32_16x16x32_bf16 v[86:89], v[222:225], v[166:169], v[86:89]
	v_mfma_f32_16x16x32_bf16 v[90:93], v[226:229], v[166:169], v[90:93]
	v_mfma_f32_16x16x32_bf16 v[94:97], v[230:233], v[166:169], v[94:97]
	v_mfma_f32_16x16x32_bf16 v[98:101], v[218:221], v[170:173], v[98:101]
	v_mfma_f32_16x16x32_bf16 v[102:105], v[222:225], v[170:173], v[102:105]
	v_mfma_f32_16x16x32_bf16 v[106:109], v[226:229], v[170:173], v[106:109]
	v_mfma_f32_16x16x32_bf16 v[110:113], v[230:233], v[170:173], v[110:113]
	v_mfma_f32_16x16x32_bf16 v[114:117], v[218:221], v[174:177], v[114:117]
	v_mfma_f32_16x16x32_bf16 v[118:121], v[222:225], v[174:177], v[118:121]
	v_mfma_f32_16x16x32_bf16 v[122:125], v[226:229], v[174:177], v[122:125]
	v_mfma_f32_16x16x32_bf16 v[126:129], v[230:233], v[174:177], v[126:129]
	ds_read_b128 v[218:221], v140 offset:8192
	ds_read_b128 v[222:225], v140 offset:9216
	ds_read_b128 v[226:229], v140 offset:10240
	ds_read_b128 v[230:233], v140 offset:11264
	s_waitcnt lgkmcnt(4)
	v_mfma_f32_16x16x32_bf16 v[62:65], v[194:197], v[178:181], v[62:65]
	v_mfma_f32_16x16x32_bf16 v[58:61], v[198:201], v[178:181], v[58:61]
	v_mfma_f32_16x16x32_bf16 v[54:57], v[202:205], v[178:181], v[54:57]
	v_mfma_f32_16x16x32_bf16 v[50:53], v[206:209], v[178:181], v[50:53]
	v_mfma_f32_16x16x32_bf16 v[46:49], v[194:197], v[182:185], v[46:49]
	v_mfma_f32_16x16x32_bf16 v[42:45], v[198:201], v[182:185], v[42:45]
	v_mfma_f32_16x16x32_bf16 v[38:41], v[202:205], v[182:185], v[38:41]
	v_mfma_f32_16x16x32_bf16 v[34:37], v[206:209], v[182:185], v[34:37]
	v_mfma_f32_16x16x32_bf16 v[30:33], v[194:197], v[186:189], v[30:33]
	v_mfma_f32_16x16x32_bf16 v[26:29], v[198:201], v[186:189], v[26:29]
	v_mfma_f32_16x16x32_bf16 v[22:25], v[202:205], v[186:189], v[22:25]
	v_mfma_f32_16x16x32_bf16 v[18:21], v[206:209], v[186:189], v[18:21]
	v_mfma_f32_16x16x32_bf16 v[14:17], v[194:197], v[190:193], v[14:17]
	v_mfma_f32_16x16x32_bf16 v[10:13], v[198:201], v[190:193], v[10:13]
	v_mfma_f32_16x16x32_bf16 v[6:9], v[202:205], v[190:193], v[6:9]
	v_mfma_f32_16x16x32_bf16 v[2:5], v[206:209], v[190:193], v[2:5]
	s_waitcnt lgkmcnt(0)
	v_mfma_f32_16x16x32_bf16 v[66:69], v[218:221], v[178:181], v[66:69]
	v_mfma_f32_16x16x32_bf16 v[70:73], v[222:225], v[178:181], v[70:73]
	v_mfma_f32_16x16x32_bf16 v[74:77], v[226:229], v[178:181], v[74:77]
	v_mfma_f32_16x16x32_bf16 v[78:81], v[230:233], v[178:181], v[78:81]
	v_mfma_f32_16x16x32_bf16 v[82:85], v[218:221], v[182:185], v[82:85]
	v_mfma_f32_16x16x32_bf16 v[86:89], v[222:225], v[182:185], v[86:89]
	v_mfma_f32_16x16x32_bf16 v[90:93], v[226:229], v[182:185], v[90:93]
	v_mfma_f32_16x16x32_bf16 v[94:97], v[230:233], v[182:185], v[94:97]
	v_mfma_f32_16x16x32_bf16 v[98:101], v[218:221], v[186:189], v[98:101]
	v_mfma_f32_16x16x32_bf16 v[102:105], v[222:225], v[186:189], v[102:105]
	v_mfma_f32_16x16x32_bf16 v[106:109], v[226:229], v[186:189], v[106:109]
	v_mfma_f32_16x16x32_bf16 v[110:113], v[230:233], v[186:189], v[110:113]
	v_mfma_f32_16x16x32_bf16 v[114:117], v[218:221], v[190:193], v[114:117]
	v_mfma_f32_16x16x32_bf16 v[118:121], v[222:225], v[190:193], v[118:121]
	v_mfma_f32_16x16x32_bf16 v[122:125], v[226:229], v[190:193], v[122:125]
	v_mfma_f32_16x16x32_bf16 v[126:129], v[230:233], v[190:193], v[126:129]
.Lpk_gw_kdone2:
	s_nop 7
	s_nop 1
	s_barrier
	ds_write_b128 v245, v[66:69] offset:0
	ds_write_b128 v245, v[70:73] offset:1024
	ds_write_b128 v245, v[74:77] offset:2048
	ds_write_b128 v245, v[78:81] offset:3072
	ds_write_b128 v245, v[82:85] offset:4096
	ds_write_b128 v245, v[86:89] offset:5120
	ds_write_b128 v245, v[90:93] offset:6144
	ds_write_b128 v245, v[94:97] offset:7168
	ds_write_b128 v245, v[98:101] offset:8192
	ds_write_b128 v245, v[102:105] offset:9216
	ds_write_b128 v245, v[106:109] offset:10240
	ds_write_b128 v245, v[110:113] offset:11264
	ds_write_b128 v245, v[114:117] offset:12288
	ds_write_b128 v245, v[118:121] offset:13312
	ds_write_b128 v245, v[122:125] offset:14336
	ds_write_b128 v245, v[126:129] offset:15360
	s_waitcnt lgkmcnt(0)
	s_branch .Lgw_done
.Lgw_single:
	v_mov_b32_e32 v62, 0
	v_mov_b32_e32 v63, 0
	v_mov_b32_e32 v64, 0
	v_mov_b32_e32 v65, 0
	v_mov_b32_e32 v58, 0
	v_mov_b32_e32 v59, 0
	v_mov_b32_e32 v60, 0
	v_mov_b32_e32 v61, 0
	v_mov_b32_e32 v54, 0
	v_mov_b32_e32 v55, 0
	v_mov_b32_e32 v56, 0
	v_mov_b32_e32 v57, 0
	v_mov_b32_e32 v50, 0
	v_mov_b32_e32 v51, 0
	v_mov_b32_e32 v52, 0
	v_mov_b32_e32 v53, 0
	v_mov_b32_e32 v46, 0
	v_mov_b32_e32 v47, 0
	v_mov_b32_e32 v48, 0
	v_mov_b32_e32 v49, 0
	v_mov_b32_e32 v42, 0
	v_mov_b32_e32 v43, 0
	v_mov_b32_e32 v44, 0
	v_mov_b32_e32 v45, 0
	v_mov_b32_e32 v38, 0
	v_mov_b32_e32 v39, 0
	v_mov_b32_e32 v40, 0
	v_mov_b32_e32 v41, 0
	v_mov_b32_e32 v34, 0
	v_mov_b32_e32 v35, 0
	v_mov_b32_e32 v36, 0
	v_mov_b32_e32 v37, 0
	v_mov_b32_e32 v30, 0
	v_mov_b32_e32 v31, 0
	v_mov_b32_e32 v32, 0
	v_mov_b32_e32 v33, 0
	v_mov_b32_e32 v26, 0
	v_mov_b32_e32 v27, 0
	v_mov_b32_e32 v28, 0
	v_mov_b32_e32 v29, 0
	v_mov_b32_e32 v22, 0
	v_mov_b32_e32 v23, 0
	v_mov_b32_e32 v24, 0
	v_mov_b32_e32 v25, 0
	v_mov_b32_e32 v18, 0
	v_mov_b32_e32 v19, 0
	v_mov_b32_e32 v20, 0
	v_mov_b32_e32 v21, 0
	v_mov_b32_e32 v14, 0
	v_mov_b32_e32 v15, 0
	v_mov_b32_e32 v16, 0
	v_mov_b32_e32 v17, 0
	v_mov_b32_e32 v10, 0
	v_mov_b32_e32 v11, 0
	v_mov_b32_e32 v12, 0
	v_mov_b32_e32 v13, 0
	v_mov_b32_e32 v6, 0
	v_mov_b32_e32 v7, 0
	v_mov_b32_e32 v8, 0
	v_mov_b32_e32 v9, 0
	v_mov_b32_e32 v2, 0
	v_mov_b32_e32 v3, 0
	v_mov_b32_e32 v4, 0
	v_mov_b32_e32 v5, 0
	s_add_u32 m0, s20, 0x0
	s_nop 0
	global_load_lds_dwordx4 v137, s[4:5]
	s_add_u32 m0, s20, 0x2000
	s_nop 0
	global_load_lds_dwordx4 v138, s[4:5]
	s_add_u32 m0, s20, 0x4000
	s_nop 0
	global_load_lds_dwordx4 v137, s[6:7]
	s_add_u32 s4, s4, 1024
	s_addc_u32 s5, s5, 0
	s_add_u32 s6, s6, 1024
	s_addc_u32 s7, s7, 0
	s_add_u32 m0, s20, 0x8000
	s_nop 0
	global_load_lds_dwordx4 v137, s[4:5]
	s_add_u32 m0, s20, 0xa000
	s_nop 0
	global_load_lds_dwordx4 v138, s[4:5]
	s_add_u32 m0, s20, 0xc000
	s_nop 0
	global_load_lds_dwordx4 v137, s[6:7]
	s_add_u32 s4, s4, 1024
	s_addc_u32 s5, s5, 0
	s_add_u32 s6, s6, 1024
	s_addc_u32 s7, s7, 0
	s_add_u32 m0, s20, 0x10000
	s_nop 0
	global_load_lds_dwordx4 v137, s[4:5]
	s_add_u32 m0, s20, 0x12000
	s_nop 0
	global_load_lds_dwordx4 v138, s[4:5]
	s_add_u32 m0, s20, 0x14000
	s_nop 0
	global_load_lds_dwordx4 v137, s[6:7]
	s_add_u32 s4, s4, 1024
	s_addc_u32 s5, s5, 0
	s_add_u32 s6, s6, 1024
	s_addc_u32 s7, s7, 0
	s_mov_b32 s32, 7
.Lpk_gw_ks4:
	s_waitcnt vmcnt(6)
	s_barrier
	v_add_u32_e32 v139, 0x0, v135
	v_add_u32_e32 v140, 0x0, v136
	ds_read_b128 v[162:165], v139 offset:0
	ds_read_b128 v[166:169], v139 offset:1024
	ds_read_b128 v[170:173], v139 offset:2048
	ds_read_b128 v[174:177], v139 offset:3072
	ds_read_b128 v[194:197], v140 offset:0
	ds_read_b128 v[198:201], v140 offset:1024
	ds_read_b128 v[202:205], v140 offset:2048
	ds_read_b128 v[206:209], v140 offset:3072
	s_add_u32 m0, s20, 0x18000
	s_nop 0
	global_load_lds_dwordx4 v137, s[4:5]
	s_add_u32 m0, s20, 0x1a000
	s_nop 0
	global_load_lds_dwordx4 v138, s[4:5]
	s_add_u32 m0, s20, 0x1c000
	s_nop 0
	global_load_lds_dwordx4 v137, s[6:7]
	s_add_u32 s4, s4, 1024
	s_addc_u32 s5, s5, 0
	s_add_u32 s6, s6, 1024
	s_addc_u32 s7, s7, 0
	s_waitcnt lgkmcnt(0)
	v_mfma_f32_16x16x32_bf16 v[62:65], v[194:197], v[162:165], v[62:65]
	v_mfma_f32_16x16x32_bf16 v[58:61], v[198:201], v[162:165], v[58:61]
	v_mfma_f32_16x16x32_bf16 v[54:57], v[202:205], v[162:165], v[54:57]
	v_mfma_f32_16x16x32_bf16 v[50:53], v[206:209], v[162:165], v[50:53]
	v_mfma_f32_16x16x32_bf16 v[46:49], v[194:197], v[166:169], v[46:49]
	v_mfma_f32_16x16x32_bf16 v[42:45], v[198:201], v[166:169], v[42:45]
	v_mfma_f32_16x16x32_bf16 v[38:41], v[202:205], v[166:169], v[38:41]
	v_mfma_f32_16x16x32_bf16 v[34:37], v[206:209], v[166:169], v[34:37]
	v_mfma_f32_16x16x32_bf16 v[30:33], v[194:197], v[170:173], v[30:33]
	v_mfma_f32_16x16x32_bf16 v[26:29], v[198:201], v[170:173], v[26:29]
	v_mfma_f32_16x16x32_bf16 v[22:25], v[202:205], v[170:173], v[22:25]
	v_mfma_f32_16x16x32_bf16 v[18:21], v[206:209], v[170:173], v[18:21]
	v_mfma_f32_16x16x32_bf16 v[14:17], v[194:197], v[174:177], v[14:17]
	v_mfma_f32_16x16x32_bf16 v[10:13], v[198:201], v[174:177], v[10:13]
	v_mfma_f32_16x16x32_bf16 v[6:9], v[202:205], v[174:177], v[6:9]
	v_mfma_f32_16x16x32_bf16 v[2:5], v[206:209], v[174:177], v[2:5]
	s_waitcnt vmcnt(6)
	s_barrier
	v_add_u32_e32 v139, 0x8000, v135
	v_add_u32_e32 v140, 0x8000, v136
	ds_read_b128 v[162:165], v139 offset:0
	ds_read_b128 v[166:169], v139 offset:1024
	ds_read_b128 v[170:173], v139 offset:2048
	ds_read_b128 v[174:177], v139 offset:3072
	ds_read_b128 v[194:197], v140 offset:0
	ds_read_b128 v[198:201], v140 offset:1024
	ds_read_b128 v[202:205], v140 offset:2048
	ds_read_b128 v[206:209], v140 offset:3072
	s_add_u32 m0, s20, 0x0
	s_nop 0
	global_load_lds_dwordx4 v137, s[4:5]
	s_add_u32 m0, s20, 0x2000
	s_nop 0
	global_load_lds_dwordx4 v138, s[4:5]
	s_add_u32 m0, s20, 0x4000
	s_nop 0
	global_load_lds_dwordx4 v137, s[6:7]
	s_add_u32 s4, s4, 1024
	s_addc_u32 s5, s5, 0
	s_add_u32 s6, s6, 1024
	s_addc_u32 s7, s7, 0
	s_waitcnt lgkmcnt(0)
	v_mfma_f32_16x16x32_bf16 v[62:65], v[194:197], v[162:165], v[62:65]
	v_mfma_f32_16x16x32_bf16 v[58:61], v[198:201], v[162:165], v[58:61]
	v_mfma_f32_16x16x32_bf16 v[54:57], v[202:205], v[162:165], v[54:57]
	v_mfma_f32_16x16x32_bf16 v[50:53], v[206:209], v[162:165], v[50:53]
	v_mfma_f32_16x16x32_bf16 v[46:49], v[194:197], v[166:169], v[46:49]
	v_mfma_f32_16x16x32_bf16 v[42:45], v[198:201], v[166:169], v[42:45]
	v_mfma_f32_16x16x32_bf16 v[38:41], v[202:205], v[166:169], v[38:41]
	v_mfma_f32_16x16x32_bf16 v[34:37], v[206:209], v[166:169], v[34:37]
	v_mfma_f32_16x16x32_bf16 v[30:33], v[194:197], v[170:173], v[30:33]
	v_mfma_f32_16x16x32_bf16 v[26:29], v[198:201], v[170:173], v[26:29]
	v_mfma_f32_16x16x32_bf16 v[22:25], v[202:205], v[170:173], v[22:25]
	v_mfma_f32_16x16x32_bf16 v[18:21], v[206:209], v[170:173], v[18:21]
	v_mfma_f32_16x16x32_bf16 v[14:17], v[194:197], v[174:177], v[14:17]
	v_mfma_f32_16x16x32_bf16 v[10:13], v[198:201], v[174:177], v[10:13]
	v_mfma_f32_16x16x32_bf16 v[6:9], v[202:205], v[174:177], v[6:9]
	v_mfma_f32_16x16x32_bf16 v[2:5], v[206:209], v[174:177], v[2:5]
	s_waitcnt vmcnt(6)
	s_barrier
	v_add_u32_e32 v139, 0x10000, v135
	v_add_u32_e32 v140, 0x10000, v136
	ds_read_b128 v[162:165], v139 offset:0
	ds_read_b128 v[166:169], v139 offset:1024
	ds_read_b128 v[170:173], v139 offset:2048
	ds_read_b128 v[174:177], v139 offset:3072
	ds_read_b128 v[194:197], v140 offset:0
	ds_read_b128 v[198:201], v140 offset:1024
	ds_read_b128 v[202:205], v140 offset:2048
	ds_read_b128 v[206:209], v140 offset:3072
	s_add_u32 m0, s20, 0x8000
	s_nop 0
	global_load_lds_dwordx4 v137, s[4:5]
	s_add_u32 m0, s20, 0xa000
	s_nop 0
	global_load_lds_dwordx4 v138, s[4:5]
	s_add_u32 m0, s20, 0xc000
	s_nop 0
	global_load_lds_dwordx4 v137, s[6:7]
	s_add_u32 s4, s4, 1024
	s_addc_u32 s5, s5, 0
	s_add_u32 s6, s6, 1024
	s_addc_u32 s7, s7, 0
	s_waitcnt lgkmcnt(0)
	v_mfma_f32_16x16x32_bf16 v[62:65], v[194:197], v[162:165], v[62:65]
	v_mfma_f32_16x16x32_bf16 v[58:61], v[198:201], v[162:165], v[58:61]
	v_mfma_f32_16x16x32_bf16 v[54:57], v[202:205], v[162:165], v[54:57]
	v_mfma_f32_16x16x32_bf16 v[50:53], v[206:209], v[162:165], v[50:53]
	v_mfma_f32_16x16x32_bf16 v[46:49], v[194:197], v[166:169], v[46:49]
	v_mfma_f32_16x16x32_bf16 v[42:45], v[198:201], v[166:169], v[42:45]
	v_mfma_f32_16x16x32_bf16 v[38:41], v[202:205], v[166:169], v[38:41]
	v_mfma_f32_16x16x32_bf16 v[34:37], v[206:209], v[166:169], v[34:37]
	v_mfma_f32_16x16x32_bf16 v[30:33], v[194:197], v[170:173], v[30:33]
	v_mfma_f32_16x16x32_bf16 v[26:29], v[198:201], v[170:173], v[26:29]
	v_mfma_f32_16x16x32_bf16 v[22:25], v[202:205], v[170:173], v[22:25]
	v_mfma_f32_16x16x32_bf16 v[18:21], v[206:209], v[170:173], v[18:21]
	v_mfma_f32_16x16x32_bf16 v[14:17], v[194:197], v[174:177], v[14:17]
	v_mfma_f32_16x16x32_bf16 v[10:13], v[198:201], v[174:177], v[10:13]
	v_mfma_f32_16x16x32_bf16 v[6:9], v[202:205], v[174:177], v[6:9]
	v_mfma_f32_16x16x32_bf16 v[2:5], v[206:209], v[174:177], v[2:5]
	s_waitcnt vmcnt(6)
	s_barrier
	v_add_u32_e32 v139, 0x18000, v135
	v_add_u32_e32 v140, 0x18000, v136
	ds_read_b128 v[162:165], v139 offset:0
	ds_read_b128 v[166:169], v139 offset:1024
	ds_read_b128 v[170:173], v139 offset:2048
	ds_read_b128 v[174:177], v139 offset:3072
	ds_read_b128 v[194:197], v140 offset:0
	ds_read_b128 v[198:201], v140 offset:1024
	ds_read_b128 v[202:205], v140 offset:2048
	ds_read_b128 v[206:209], v140 offset:3072
	s_add_u32 m0, s20, 0x10000
	s_nop 0
	global_load_lds_dwordx4 v137, s[4:5]
	s_add_u32 m0, s20, 0x12000
	s_nop 0
	global_load_lds_dwordx4 v138, s[4:5]
	s_add_u32 m0, s20, 0x14000
	s_nop 0
	global_load_lds_dwordx4 v137, s[6:7]
	s_add_u32 s4, s4, 1024
	s_addc_u32 s5, s5, 0
	s_add_u32 s6, s6, 1024
	s_addc_u32 s7, s7, 0
	s_waitcnt lgkmcnt(0)
	v_mfma_f32_16x16x32_bf16 v[62:65], v[194:197], v[162:165], v[62:65]
	v_mfma_f32_16x16x32_bf16 v[58:61], v[198:201], v[162:165], v[58:61]
	v_mfma_f32_16x16x32_bf16 v[54:57], v[202:205], v[162:165], v[54:57]
	v_mfma_f32_16x16x32_bf16 v[50:53], v[206:209], v[162:165], v[50:53]
	v_mfma_f32_16x16x32_bf16 v[46:49], v[194:197], v[166:169], v[46:49]
	v_mfma_f32_16x16x32_bf16 v[42:45], v[198:201], v[166:169], v[42:45]
	v_mfma_f32_16x16x32_bf16 v[38:41], v[202:205], v[166:169], v[38:41]
	v_mfma_f32_16x16x32_bf16 v[34:37], v[206:209], v[166:169], v[34:37]
	v_mfma_f32_16x16x32_bf16 v[30:33], v[194:197], v[170:173], v[30:33]
	v_mfma_f32_16x16x32_bf16 v[26:29], v[198:201], v[170:173], v[26:29]
	v_mfma_f32_16x16x32_bf16 v[22:25], v[202:205], v[170:173], v[22:25]
	v_mfma_f32_16x16x32_bf16 v[18:21], v[206:209], v[170:173], v[18:21]
	v_mfma_f32_16x16x32_bf16 v[14:17], v[194:197], v[174:177], v[14:17]
	v_mfma_f32_16x16x32_bf16 v[10:13], v[198:201], v[174:177], v[10:13]
	v_mfma_f32_16x16x32_bf16 v[6:9], v[202:205], v[174:177], v[6:9]
	v_mfma_f32_16x16x32_bf16 v[2:5], v[206:209], v[174:177], v[2:5]
	s_sub_u32 s32, s32, 1
	s_cmp_lg_u32 s32, 0
	s_cbranch_scc1 .Lpk_gw_ks4
	s_waitcnt vmcnt(6)
	s_barrier
	v_add_u32_e32 v139, 0x0, v135
	v_add_u32_e32 v140, 0x0, v136
	ds_read_b128 v[162:165], v139 offset:0
	ds_read_b128 v[166:169], v139 offset:1024
	ds_read_b128 v[170:173], v139 offset:2048
	ds_read_b128 v[174:177], v139 offset:3072
	ds_read_b128 v[194:197], v140 offset:0
	ds_read_b128 v[198:201], v140 offset:1024
	ds_read_b128 v[202:205], v140 offset:2048
	ds_read_b128 v[206:209], v140 offset:3072
	s_add_u32 m0, s20, 0x18000
	s_nop 0
	global_load_lds_dwordx4 v137, s[4:5]
	s_add_u32 m0, s20, 0x1a000
	s_nop 0
	global_load_lds_dwordx4 v138, s[4:5]
	s_add_u32 m0, s20, 0x1c000
	s_nop 0
	global_load_lds_dwordx4 v137, s[6:7]
	s_add_u32 s4, s4, 1024
	s_addc_u32 s5, s5, 0
	s_add_u32 s6, s6, 1024
	s_addc_u32 s7, s7, 0
	s_waitcnt lgkmcnt(0)
	v_mfma_f32_16x16x32_bf16 v[62:65], v[194:197], v[162:165], v[62:65]
	v_mfma_f32_16x16x32_bf16 v[58:61], v[198:201], v[162:165], v[58:61]
	v_mfma_f32_16x16x32_bf16 v[54:57], v[202:205], v[162:165], v[54:57]
	v_mfma_f32_16x16x32_bf16 v[50:53], v[206:209], v[162:165], v[50:53]
	v_mfma_f32_16x16x32_bf16 v[46:49], v[194:197], v[166:169], v[46:49]
	v_mfma_f32_16x16x32_bf16 v[42:45], v[198:201], v[166:169], v[42:45]
	v_mfma_f32_16x16x32_bf16 v[38:41], v[202:205], v[166:169], v[38:41]
	v_mfma_f32_16x16x32_bf16 v[34:37], v[206:209], v[166:169], v[34:37]
	v_mfma_f32_16x16x32_bf16 v[30:33], v[194:197], v[170:173], v[30:33]
	v_mfma_f32_16x16x32_bf16 v[26:29], v[198:201], v[170:173], v[26:29]
	v_mfma_f32_16x16x32_bf16 v[22:25], v[202:205], v[170:173], v[22:25]
	v_mfma_f32_16x16x32_bf16 v[18:21], v[206:209], v[170:173], v[18:21]
	v_mfma_f32_16x16x32_bf16 v[14:17], v[194:197], v[174:177], v[14:17]
	v_mfma_f32_16x16x32_bf16 v[10:13], v[198:201], v[174:177], v[10:13]
	v_mfma_f32_16x16x32_bf16 v[6:9], v[202:205], v[174:177], v[6:9]
	v_mfma_f32_16x16x32_bf16 v[2:5], v[206:209], v[174:177], v[2:5]
	s_waitcnt vmcnt(6)
	s_barrier
	v_add_u32_e32 v139, 0x8000, v135
	v_add_u32_e32 v140, 0x8000, v136
	ds_read_b128 v[162:165], v139 offset:0
	ds_read_b128 v[166:169], v139 offset:1024
	ds_read_b128 v[170:173], v139 offset:2048
	ds_read_b128 v[174:177], v139 offset:3072
	ds_read_b128 v[194:197], v140 offset:0
	ds_read_b128 v[198:201], v140 offset:1024
	ds_read_b128 v[202:205], v140 offset:2048
	ds_read_b128 v[206:209], v140 offset:3072
	s_waitcnt lgkmcnt(0)
	v_mfma_f32_16x16x32_bf16 v[62:65], v[194:197], v[162:165], v[62:65]
	v_mfma_f32_16x16x32_bf16 v[58:61], v[198:201], v[162:165], v[58:61]
	v_mfma_f32_16x16x32_bf16 v[54:57], v[202:205], v[162:165], v[54:57]
	v_mfma_f32_16x16x32_bf16 v[50:53], v[206:209], v[162:165], v[50:53]
	v_mfma_f32_16x16x32_bf16 v[46:49], v[194:197], v[166:169], v[46:49]
	v_mfma_f32_16x16x32_bf16 v[42:45], v[198:201], v[166:169], v[42:45]
	v_mfma_f32_16x16x32_bf16 v[38:41], v[202:205], v[166:169], v[38:41]
	v_mfma_f32_16x16x32_bf16 v[34:37], v[206:209], v[166:169], v[34:37]
	v_mfma_f32_16x16x32_bf16 v[30:33], v[194:197], v[170:173], v[30:33]
	v_mfma_f32_16x16x32_bf16 v[26:29], v[198:201], v[170:173], v[26:29]
	v_mfma_f32_16x16x32_bf16 v[22:25], v[202:205], v[170:173], v[22:25]
	v_mfma_f32_16x16x32_bf16 v[18:21], v[206:209], v[170:173], v[18:21]
	v_mfma_f32_16x16x32_bf16 v[14:17], v[194:197], v[174:177], v[14:17]
	v_mfma_f32_16x16x32_bf16 v[10:13], v[198:201], v[174:177], v[10:13]
	v_mfma_f32_16x16x32_bf16 v[6:9], v[202:205], v[174:177], v[6:9]
	v_mfma_f32_16x16x32_bf16 v[2:5], v[206:209], v[174:177], v[2:5]
	s_waitcnt vmcnt(3)
	s_barrier
	v_add_u32_e32 v139, 0x10000, v135
	v_add_u32_e32 v140, 0x10000, v136
	ds_read_b128 v[162:165], v139 offset:0
	ds_read_b128 v[166:169], v139 offset:1024
	ds_read_b128 v[170:173], v139 offset:2048
	ds_read_b128 v[174:177], v139 offset:3072
	ds_read_b128 v[194:197], v140 offset:0
	ds_read_b128 v[198:201], v140 offset:1024
	ds_read_b128 v[202:205], v140 offset:2048
	ds_read_b128 v[206:209], v140 offset:3072
	s_waitcnt lgkmcnt(0)
	v_mfma_f32_16x16x32_bf16 v[62:65], v[194:197], v[162:165], v[62:65]
	v_mfma_f32_16x16x32_bf16 v[58:61], v[198:201], v[162:165], v[58:61]
	v_mfma_f32_16x16x32_bf16 v[54:57], v[202:205], v[162:165], v[54:57]
	v_mfma_f32_16x16x32_bf16 v[50:53], v[206:209], v[162:165], v[50:53]
	v_mfma_f32_16x16x32_bf16 v[46:49], v[194:197], v[166:169], v[46:49]
	v_mfma_f32_16x16x32_bf16 v[42:45], v[198:201], v[166:169], v[42:45]
	v_mfma_f32_16x16x32_bf16 v[38:41], v[202:205], v[166:169], v[38:41]
	v_mfma_f32_16x16x32_bf16 v[34:37], v[206:209], v[166:169], v[34:37]
	v_mfma_f32_16x16x32_bf16 v[30:33], v[194:197], v[170:173], v[30:33]
	v_mfma_f32_16x16x32_bf16 v[26:29], v[198:201], v[170:173], v[26:29]
	v_mfma_f32_16x16x32_bf16 v[22:25], v[202:205], v[170:173], v[22:25]
	v_mfma_f32_16x16x32_bf16 v[18:21], v[206:209], v[170:173], v[18:21]
	v_mfma_f32_16x16x32_bf16 v[14:17], v[194:197], v[174:177], v[14:17]
	v_mfma_f32_16x16x32_bf16 v[10:13], v[198:201], v[174:177], v[10:13]
	v_mfma_f32_16x16x32_bf16 v[6:9], v[202:205], v[174:177], v[6:9]
	v_mfma_f32_16x16x32_bf16 v[2:5], v[206:209], v[174:177], v[2:5]
	s_waitcnt vmcnt(0)
	s_barrier
	v_add_u32_e32 v139, 0x18000, v135
	v_add_u32_e32 v140, 0x18000, v136
	ds_read_b128 v[162:165], v139 offset:0
	ds_read_b128 v[166:169], v139 offset:1024
	ds_read_b128 v[170:173], v139 offset:2048
	ds_read_b128 v[174:177], v139 offset:3072
	ds_read_b128 v[194:197], v140 offset:0
	ds_read_b128 v[198:201], v140 offset:1024
	ds_read_b128 v[202:205], v140 offset:2048
	ds_read_b128 v[206:209], v140 offset:3072
	s_waitcnt lgkmcnt(0)
	v_mfma_f32_16x16x32_bf16 v[62:65], v[194:197], v[162:165], v[62:65]
	v_mfma_f32_16x16x32_bf16 v[58:61], v[198:201], v[162:165], v[58:61]
	v_mfma_f32_16x16x32_bf16 v[54:57], v[202:205], v[162:165], v[54:57]
	v_mfma_f32_16x16x32_bf16 v[50:53], v[206:209], v[162:165], v[50:53]
	v_mfma_f32_16x16x32_bf16 v[46:49], v[194:197], v[166:169], v[46:49]
	v_mfma_f32_16x16x32_bf16 v[42:45], v[198:201], v[166:169], v[42:45]
	v_mfma_f32_16x16x32_bf16 v[38:41], v[202:205], v[166:169], v[38:41]
	v_mfma_f32_16x16x32_bf16 v[34:37], v[206:209], v[166:169], v[34:37]
	v_mfma_f32_16x16x32_bf16 v[30:33], v[194:197], v[170:173], v[30:33]
	v_mfma_f32_16x16x32_bf16 v[26:29], v[198:201], v[170:173], v[26:29]
	v_mfma_f32_16x16x32_bf16 v[22:25], v[202:205], v[170:173], v[22:25]
	v_mfma_f32_16x16x32_bf16 v[18:21], v[206:209], v[170:173], v[18:21]
	v_mfma_f32_16x16x32_bf16 v[14:17], v[194:197], v[174:177], v[14:17]
	v_mfma_f32_16x16x32_bf16 v[10:13], v[198:201], v[174:177], v[10:13]
	v_mfma_f32_16x16x32_bf16 v[6:9], v[202:205], v[174:177], v[6:9]
	v_mfma_f32_16x16x32_bf16 v[2:5], v[206:209], v[174:177], v[2:5]
	s_nop 7
	s_nop 1
	s_branch .Lgw_done
.Lgw_restore:
	ds_read_b128 v[62:65], v245 offset:0
	ds_read_b128 v[58:61], v245 offset:1024
	ds_read_b128 v[54:57], v245 offset:2048
	ds_read_b128 v[50:53], v245 offset:3072
	ds_read_b128 v[46:49], v245 offset:4096
	ds_read_b128 v[42:45], v245 offset:5120
	ds_read_b128 v[38:41], v245 offset:6144
	ds_read_b128 v[34:37], v245 offset:7168
	ds_read_b128 v[30:33], v245 offset:8192
	ds_read_b128 v[26:29], v245 offset:9216
	ds_read_b128 v[22:25], v245 offset:10240
	ds_read_b128 v[18:21], v245 offset:11264
	ds_read_b128 v[14:17], v245 offset:12288
	ds_read_b128 v[10:13], v245 offset:13312
	ds_read_b128 v[6:9], v245 offset:14336
	ds_read_b128 v[2:5], v245 offset:15360
	s_waitcnt lgkmcnt(0)
.Lgw_done:
	v_bfe_u32 v161, v0, 6, 1
	v_and_b32_e32 v134, 15, v0
	v_bfe_u32 v162, v0, 4, 2
	s_nop 1
	v_ashrrev_i32_e32 v0, 1, v0
	v_and_b32_e32 v163, 0xffffffc0, v0
	s_cmp_gt_i32 s18, 7
	s_mov_b64 s[4:5], -1
	s_cbranch_scc0 .LBB0_316
	s_cmp_gt_u32 s18, 15
	s_cbranch_scc0 .LBB0_305
	s_cmpk_gt_i32 s16, 0x6f
	s_cselect_b64 s[4:5], -1, 0
	s_add_i32 s3, s2, 0xfffff000
	s_lshr_b32 s3, s3, 10
	s_cmpk_lt_i32 s16, 0x70
	s_cselect_b64 s[6:7], -1, 0
	s_and_b64 s[8:9], s[6:7], exec
	s_movk_i32 s8, 0x70
	s_cselect_b32 s8, s8, 0x300
	s_and_b32 s8, s8, s2
	v_add_u32_e32 v136, s8, v163
	s_cmp_gt_u32 s18, 31
	s_mov_b64 s[8:9], -1
	s_cbranch_scc0 .LBB0_290
	s_cmp_gt_u32 s18, 39
	s_cbranch_scc0 .LBB0_283
	v_or_b32_e32 v0, s2, v134
	v_add_u32_e32 v66, v0, v163
	v_ashrrev_i32_e32 v67, 31, v66
	v_lshlrev_b64 v[68:69], 12, v[66:67]
	v_mul_f32_e32 v67, 0xbfb8aa3b, v62
	v_mul_f32_e32 v74, 0xbfb8aa3b, v63
	v_mul_f32_e32 v75, 0xbfb8aa3b, v64
	v_mul_f32_e32 v76, 0xbfb8aa3b, v65
	v_exp_f32_e32 v67, v67
	v_exp_f32_e32 v74, v74
	v_exp_f32_e32 v75, v75
	v_exp_f32_e32 v76, v76
	s_lshl_b64 s[8:9], s[40:41], 1
	s_add_u32 s8, s48, s8
	s_addc_u32 s9, s49, s9
	v_add_f32_e32 v67, 1.0, v67
	v_add_f32_e32 v74, 1.0, v74
	v_add_f32_e32 v75, 1.0, v75
	v_add_f32_e32 v76, 1.0, v76
	v_lshl_add_u64 v[68:69], s[8:9], 0, v[68:69]
	v_lshlrev_b32_e32 v0, 7, v161
	v_rcp_f32_e32 v67, v67
	v_rcp_f32_e32 v74, v74
	v_rcp_f32_e32 v75, v75
	v_rcp_f32_e32 v76, v76
	v_lshl_add_u64 v[70:71], v[68:69], 0, v[0:1]
	v_lshlrev_b32_e32 v68, 3, v162
	v_mov_b32_e32 v69, v1
	v_lshl_add_u64 v[72:73], v[70:71], 0, v[68:69]
	s_mov_b64 s[38:39], 0xa15d800
	s_mov_b32 s10, 0xa15d000
	v_lshl_add_u64 v[70:71], v[72:73], 0, s[38:39]
	v_add_co_u32_e32 v72, vcc, s10, v72
	v_cvt_pk_bf16_f32 v74, v67, v74
	v_cvt_pk_bf16_f32 v75, v75, v76
	v_addc_co_u32_e32 v73, vcc, 0, v73, vcc
	global_store_dwordx2 v[72:73], v[74:75], off offset:2048
	v_mul_f32_e32 v67, 0xbfb8aa3b, v58
	v_mul_f32_e32 v72, 0xbfb8aa3b, v59
	v_mul_f32_e32 v73, 0xbfb8aa3b, v60
	v_mul_f32_e32 v74, 0xbfb8aa3b, v61
	v_exp_f32_e32 v67, v67
	v_exp_f32_e32 v72, v72
	v_exp_f32_e32 v73, v73
	v_exp_f32_e32 v74, v74
	v_add_f32_e32 v67, 1.0, v67
	v_add_f32_e32 v72, 1.0, v72
	v_add_f32_e32 v73, 1.0, v73
	v_add_f32_e32 v74, 1.0, v74
	v_rcp_f32_e32 v67, v67
	v_rcp_f32_e32 v72, v72
	v_rcp_f32_e32 v73, v73
	v_rcp_f32_e32 v74, v74
	v_mul_f32_e32 v75, 0xbfb8aa3b, v48
	v_cvt_pk_bf16_f32 v72, v67, v72
	v_mul_f32_e32 v67, 0xbfb8aa3b, v54
	v_cvt_pk_bf16_f32 v73, v73, v74
	global_store_dwordx2 v[70:71], v[72:73], off offset:32
	v_mul_f32_e32 v72, 0xbfb8aa3b, v55
	v_mul_f32_e32 v73, 0xbfb8aa3b, v56
	v_mul_f32_e32 v74, 0xbfb8aa3b, v57
	v_exp_f32_e32 v67, v67
	v_exp_f32_e32 v72, v72
	v_exp_f32_e32 v73, v73
	v_exp_f32_e32 v74, v74
	v_add_f32_e32 v67, 1.0, v67
	v_add_f32_e32 v72, 1.0, v72
	v_add_f32_e32 v73, 1.0, v73
	v_add_f32_e32 v74, 1.0, v74
	v_rcp_f32_e32 v67, v67
	v_rcp_f32_e32 v72, v72
	v_rcp_f32_e32 v73, v73
	v_rcp_f32_e32 v74, v74
	v_mul_f32_e32 v76, 0xbfb8aa3b, v49
	v_cvt_pk_bf16_f32 v72, v67, v72
	v_mul_f32_e32 v67, 0xbfb8aa3b, v50
	v_cvt_pk_bf16_f32 v73, v73, v74
	global_store_dwordx2 v[70:71], v[72:73], off offset:64
	v_mul_f32_e32 v72, 0xbfb8aa3b, v51
	v_mul_f32_e32 v73, 0xbfb8aa3b, v52
	v_mul_f32_e32 v74, 0xbfb8aa3b, v53
	v_exp_f32_e32 v67, v67
	v_exp_f32_e32 v72, v72
	v_exp_f32_e32 v73, v73
	v_exp_f32_e32 v74, v74
	v_add_f32_e32 v67, 1.0, v67
	v_add_f32_e32 v72, 1.0, v72
	v_add_f32_e32 v73, 1.0, v73
	v_add_f32_e32 v74, 1.0, v74
	v_rcp_f32_e32 v67, v67
	v_rcp_f32_e32 v72, v72
	v_rcp_f32_e32 v73, v73
	v_rcp_f32_e32 v74, v74
	v_exp_f32_e32 v75, v75
	v_cvt_pk_bf16_f32 v72, v67, v72
	v_mul_f32_e32 v67, 0xbfb8aa3b, v46
	v_cvt_pk_bf16_f32 v73, v73, v74
	v_mul_f32_e32 v74, 0xbfb8aa3b, v47
	v_exp_f32_e32 v67, v67
	v_exp_f32_e32 v74, v74
	v_exp_f32_e32 v76, v76
	global_store_dwordx2 v[70:71], v[72:73], off offset:96
	v_or_b32_e32 v70, 16, v66
	v_ashrrev_i32_e32 v71, 31, v70
	v_lshlrev_b64 v[70:71], 12, v[70:71]
	v_add_f32_e32 v67, 1.0, v67
	v_add_f32_e32 v74, 1.0, v74
	v_add_f32_e32 v75, 1.0, v75
	v_add_f32_e32 v76, 1.0, v76
	v_lshl_add_u64 v[70:71], s[8:9], 0, v[70:71]
	v_rcp_f32_e32 v67, v67
	v_rcp_f32_e32 v74, v74
	v_rcp_f32_e32 v75, v75
	v_rcp_f32_e32 v76, v76
	v_lshl_add_u64 v[70:71], v[70:71], 0, v[0:1]
	v_lshl_add_u64 v[72:73], v[70:71], 0, v[68:69]
	v_lshl_add_u64 v[70:71], v[72:73], 0, s[38:39]
	v_add_co_u32_e32 v72, vcc, s10, v72
	v_cvt_pk_bf16_f32 v74, v67, v74
	v_cvt_pk_bf16_f32 v75, v75, v76
	v_addc_co_u32_e32 v73, vcc, 0, v73, vcc
	global_store_dwordx2 v[72:73], v[74:75], off offset:2048
	v_mul_f32_e32 v67, 0xbfb8aa3b, v42
	v_mul_f32_e32 v72, 0xbfb8aa3b, v43
	v_mul_f32_e32 v73, 0xbfb8aa3b, v44
	v_mul_f32_e32 v74, 0xbfb8aa3b, v45
	v_exp_f32_e32 v67, v67
	v_exp_f32_e32 v72, v72
	v_exp_f32_e32 v73, v73
	v_exp_f32_e32 v74, v74
	v_add_f32_e32 v67, 1.0, v67
	v_add_f32_e32 v72, 1.0, v72
	v_add_f32_e32 v73, 1.0, v73
	v_add_f32_e32 v74, 1.0, v74
	v_rcp_f32_e32 v67, v67
	v_rcp_f32_e32 v72, v72
	v_rcp_f32_e32 v73, v73
	v_rcp_f32_e32 v74, v74
	v_mul_f32_e32 v75, 0xbfb8aa3b, v32
	v_cvt_pk_bf16_f32 v72, v67, v72
	v_mul_f32_e32 v67, 0xbfb8aa3b, v38
	v_cvt_pk_bf16_f32 v73, v73, v74
	global_store_dwordx2 v[70:71], v[72:73], off offset:32
	v_mul_f32_e32 v72, 0xbfb8aa3b, v39
	v_mul_f32_e32 v73, 0xbfb8aa3b, v40
	v_mul_f32_e32 v74, 0xbfb8aa3b, v41
	v_exp_f32_e32 v67, v67
	v_exp_f32_e32 v72, v72
	v_exp_f32_e32 v73, v73
	v_exp_f32_e32 v74, v74
	v_add_f32_e32 v67, 1.0, v67
	v_add_f32_e32 v72, 1.0, v72
	v_add_f32_e32 v73, 1.0, v73
	v_add_f32_e32 v74, 1.0, v74
	v_rcp_f32_e32 v67, v67
	v_rcp_f32_e32 v72, v72
	v_rcp_f32_e32 v73, v73
	v_rcp_f32_e32 v74, v74
	v_mul_f32_e32 v76, 0xbfb8aa3b, v33
	v_cvt_pk_bf16_f32 v72, v67, v72
	v_mul_f32_e32 v67, 0xbfb8aa3b, v34
	v_cvt_pk_bf16_f32 v73, v73, v74
	global_store_dwordx2 v[70:71], v[72:73], off offset:64
	v_mul_f32_e32 v72, 0xbfb8aa3b, v35
	v_mul_f32_e32 v73, 0xbfb8aa3b, v36
	v_mul_f32_e32 v74, 0xbfb8aa3b, v37
	v_exp_f32_e32 v67, v67
	v_exp_f32_e32 v72, v72
	v_exp_f32_e32 v73, v73
	v_exp_f32_e32 v74, v74
	v_add_f32_e32 v67, 1.0, v67
	v_add_f32_e32 v72, 1.0, v72
	v_add_f32_e32 v73, 1.0, v73
	v_add_f32_e32 v74, 1.0, v74
	v_rcp_f32_e32 v67, v67
	v_rcp_f32_e32 v72, v72
	v_rcp_f32_e32 v73, v73
	v_rcp_f32_e32 v74, v74
	v_exp_f32_e32 v75, v75
	v_cvt_pk_bf16_f32 v72, v67, v72
	v_mul_f32_e32 v67, 0xbfb8aa3b, v30
	v_cvt_pk_bf16_f32 v73, v73, v74
	v_mul_f32_e32 v74, 0xbfb8aa3b, v31
	v_exp_f32_e32 v67, v67
	v_exp_f32_e32 v74, v74
	v_exp_f32_e32 v76, v76
	global_store_dwordx2 v[70:71], v[72:73], off offset:96
	v_or_b32_e32 v70, 32, v66
	v_ashrrev_i32_e32 v71, 31, v70
	v_lshlrev_b64 v[70:71], 12, v[70:71]
	v_add_f32_e32 v67, 1.0, v67
	v_add_f32_e32 v74, 1.0, v74
	v_add_f32_e32 v75, 1.0, v75
	v_add_f32_e32 v76, 1.0, v76
	v_lshl_add_u64 v[70:71], s[8:9], 0, v[70:71]
	v_rcp_f32_e32 v67, v67
	v_rcp_f32_e32 v74, v74
	v_rcp_f32_e32 v75, v75
	v_rcp_f32_e32 v76, v76
	v_lshl_add_u64 v[70:71], v[70:71], 0, v[0:1]
	v_lshl_add_u64 v[72:73], v[70:71], 0, v[68:69]
	v_lshl_add_u64 v[70:71], v[72:73], 0, s[38:39]
	v_add_co_u32_e32 v72, vcc, s10, v72
	v_cvt_pk_bf16_f32 v74, v67, v74
	v_cvt_pk_bf16_f32 v75, v75, v76
	v_addc_co_u32_e32 v73, vcc, 0, v73, vcc
	global_store_dwordx2 v[72:73], v[74:75], off offset:2048
	v_mul_f32_e32 v67, 0xbfb8aa3b, v26
	v_mul_f32_e32 v72, 0xbfb8aa3b, v27
	v_mul_f32_e32 v73, 0xbfb8aa3b, v28
	v_mul_f32_e32 v74, 0xbfb8aa3b, v29
	v_exp_f32_e32 v67, v67
	v_exp_f32_e32 v72, v72
	v_exp_f32_e32 v73, v73
	v_exp_f32_e32 v74, v74
	v_add_f32_e32 v67, 1.0, v67
	v_add_f32_e32 v72, 1.0, v72
	v_add_f32_e32 v73, 1.0, v73
	v_add_f32_e32 v74, 1.0, v74
	v_rcp_f32_e32 v67, v67
	v_rcp_f32_e32 v72, v72
	v_rcp_f32_e32 v73, v73
	v_rcp_f32_e32 v74, v74
	v_or_b32_e32 v66, 48, v66
	v_cvt_pk_bf16_f32 v72, v67, v72
	v_mul_f32_e32 v67, 0xbfb8aa3b, v22
	v_cvt_pk_bf16_f32 v73, v73, v74
	global_store_dwordx2 v[70:71], v[72:73], off offset:32
	v_mul_f32_e32 v72, 0xbfb8aa3b, v23
	v_mul_f32_e32 v73, 0xbfb8aa3b, v24
	v_mul_f32_e32 v74, 0xbfb8aa3b, v25
	v_exp_f32_e32 v67, v67
	v_exp_f32_e32 v72, v72
	v_exp_f32_e32 v73, v73
	v_exp_f32_e32 v74, v74
	v_add_f32_e32 v67, 1.0, v67
	v_add_f32_e32 v72, 1.0, v72
	v_add_f32_e32 v73, 1.0, v73
	v_add_f32_e32 v74, 1.0, v74
	v_rcp_f32_e32 v67, v67
	v_rcp_f32_e32 v72, v72
	v_rcp_f32_e32 v73, v73
	v_rcp_f32_e32 v74, v74
	v_cvt_pk_bf16_f32 v72, v67, v72
	v_mul_f32_e32 v67, 0xbfb8aa3b, v18
	v_cvt_pk_bf16_f32 v73, v73, v74
	global_store_dwordx2 v[70:71], v[72:73], off offset:64
	v_mul_f32_e32 v72, 0xbfb8aa3b, v19
	v_exp_f32_e32 v67, v67
	v_exp_f32_e32 v72, v72
	v_mul_f32_e32 v73, 0xbfb8aa3b, v20
	v_mul_f32_e32 v74, 0xbfb8aa3b, v21
	v_exp_f32_e32 v73, v73
	v_exp_f32_e32 v74, v74
	v_add_f32_e32 v67, 1.0, v67
	v_add_f32_e32 v72, 1.0, v72
	v_rcp_f32_e32 v67, v67
	v_rcp_f32_e32 v72, v72
	v_add_f32_e32 v73, 1.0, v73
	v_add_f32_e32 v74, 1.0, v74
	v_rcp_f32_e32 v73, v73
	v_rcp_f32_e32 v74, v74
	v_cvt_pk_bf16_f32 v72, v67, v72
	v_ashrrev_i32_e32 v67, 31, v66
	v_lshlrev_b64 v[66:67], 12, v[66:67]
	v_cvt_pk_bf16_f32 v73, v73, v74
	v_lshl_add_u64 v[66:67], s[8:9], 0, v[66:67]
	global_store_dwordx2 v[70:71], v[72:73], off offset:96
	v_lshl_add_u64 v[66:67], v[66:67], 0, v[0:1]
	v_mul_f32_e32 v0, 0xbfb8aa3b, v14
	v_mul_f32_e32 v70, 0xbfb8aa3b, v15
	v_mul_f32_e32 v71, 0xbfb8aa3b, v16
	v_mul_f32_e32 v72, 0xbfb8aa3b, v17
	v_exp_f32_e32 v0, v0
	v_exp_f32_e32 v70, v70
	v_exp_f32_e32 v71, v71
	v_exp_f32_e32 v72, v72
	v_add_f32_e32 v0, 1.0, v0
	v_add_f32_e32 v70, 1.0, v70
	v_add_f32_e32 v71, 1.0, v71
	v_add_f32_e32 v72, 1.0, v72
	v_rcp_f32_e32 v0, v0
	v_rcp_f32_e32 v70, v70
	v_rcp_f32_e32 v71, v71
	v_rcp_f32_e32 v72, v72
	v_lshl_add_u64 v[68:69], v[66:67], 0, v[68:69]
	v_lshl_add_u64 v[66:67], v[68:69], 0, s[38:39]
	v_add_co_u32_e32 v68, vcc, s10, v68
	v_cvt_pk_bf16_f32 v70, v0, v70
	v_cvt_pk_bf16_f32 v71, v71, v72
	v_addc_co_u32_e32 v69, vcc, 0, v69, vcc
	global_store_dwordx2 v[68:69], v[70:71], off offset:2048
	v_mul_f32_e32 v0, 0xbfb8aa3b, v10
	v_mul_f32_e32 v68, 0xbfb8aa3b, v11
	v_mul_f32_e32 v69, 0xbfb8aa3b, v12
	v_mul_f32_e32 v70, 0xbfb8aa3b, v13
	v_exp_f32_e32 v0, v0
	v_exp_f32_e32 v68, v68
	v_exp_f32_e32 v69, v69
	v_exp_f32_e32 v70, v70
	v_add_f32_e32 v0, 1.0, v0
	v_add_f32_e32 v68, 1.0, v68
	v_add_f32_e32 v69, 1.0, v69
	v_add_f32_e32 v70, 1.0, v70
	v_rcp_f32_e32 v0, v0
	v_rcp_f32_e32 v68, v68
	v_rcp_f32_e32 v69, v69
	v_rcp_f32_e32 v70, v70
	s_mov_b64 s[8:9], 0
	v_cvt_pk_bf16_f32 v68, v0, v68
	v_mul_f32_e32 v0, 0xbfb8aa3b, v6
	v_cvt_pk_bf16_f32 v69, v69, v70
	global_store_dwordx2 v[66:67], v[68:69], off offset:32
	v_mul_f32_e32 v68, 0xbfb8aa3b, v7
	v_mul_f32_e32 v69, 0xbfb8aa3b, v8
	v_mul_f32_e32 v70, 0xbfb8aa3b, v9
	v_exp_f32_e32 v0, v0
	v_exp_f32_e32 v68, v68
	v_exp_f32_e32 v69, v69
	v_exp_f32_e32 v70, v70
	v_add_f32_e32 v0, 1.0, v0
	v_add_f32_e32 v68, 1.0, v68
	v_add_f32_e32 v69, 1.0, v69
	v_add_f32_e32 v70, 1.0, v70
	v_rcp_f32_e32 v0, v0
	v_rcp_f32_e32 v68, v68
	v_rcp_f32_e32 v69, v69
	v_rcp_f32_e32 v70, v70
	v_cvt_pk_bf16_f32 v68, v0, v68
	v_mul_f32_e32 v0, 0xbfb8aa3b, v2
	v_cvt_pk_bf16_f32 v69, v69, v70
	global_store_dwordx2 v[66:67], v[68:69], off offset:64
	v_mul_f32_e32 v68, 0xbfb8aa3b, v3
	v_mul_f32_e32 v69, 0xbfb8aa3b, v4
	v_mul_f32_e32 v70, 0xbfb8aa3b, v5
	v_exp_f32_e32 v0, v0
	v_exp_f32_e32 v68, v68
	v_exp_f32_e32 v69, v69
	v_exp_f32_e32 v70, v70
	v_add_f32_e32 v0, 1.0, v0
	v_add_f32_e32 v68, 1.0, v68
	v_add_f32_e32 v69, 1.0, v69
	v_add_f32_e32 v70, 1.0, v70
	v_rcp_f32_e32 v0, v0
	v_rcp_f32_e32 v68, v68
	v_rcp_f32_e32 v69, v69
	v_rcp_f32_e32 v70, v70
	v_cvt_pk_bf16_f32 v68, v0, v68
	v_cvt_pk_bf16_f32 v69, v69, v70
	global_store_dwordx2 v[66:67], v[68:69], off offset:96
